# v17 + adaLN modulation GEMV in phase_init: 8-iteration deep weight prefetch ring (32 loads in flight per wave), scalar row addressing
# baseline (speedup 1.0000x reference)
; __device__ __forceinline__ void phase_init(const Params& P, unsigned char* lds) {
;     ...
;     for (int it = blk; it < DEPTH * (MODW / 64); it += G) {
;         const int l = it / (MODW / 64), n0 = (it % (MODW / 64)) * 64;
;         const float* W = P.w_mod + (size_t)l * DM * MODW + n0 + lane;
;         float acc[17];
; #pragma unroll
;         for (int bb = 0; bb < 17; ++bb) acc[bb] = 0.f;
;         for (int k = wave * 128; k < wave * 128 + 128; k += 4) {
;             const float w0 = W[(size_t)k * MODW], w1 = W[(size_t)(k + 1) * MODW], w2 = W[(size_t)(k + 2) * MODW], w3 = W[(size_t)(k + 3) * MODW];
; #pragma unroll
;             for (int bb = 0; bb < 17; ++bb) { const f32x4 s4 = *(const f32x4*)(sc + bb * DM + k); acc[bb] += s4.x * w0 + s4.y * w1 + s4.z * w2 + s4.w * w3; }
;         }
.LBB0_34:
	v_readfirstlane_b32 s4, v42
	v_readfirstlane_b32 s5, v43
	s_nop 3
	s_add_u32 s4, s4, s18
	s_addc_u32 s5, s5, -1
	global_load_dword v62, v32, s[4:5]
	s_add_u32 s4, s4, 0x6000
	s_addc_u32 s5, s5, 0
	global_load_dword v63, v32, s[4:5]
	s_add_u32 s4, s4, 0x6000
	s_addc_u32 s5, s5, 0
	global_load_dword v64, v32, s[4:5]
	s_add_u32 s4, s4, 0x6000
	s_addc_u32 s5, s5, 0
	global_load_dword v65, v32, s[4:5]
	s_add_u32 s4, s4, 0x6000
	s_addc_u32 s5, s5, 0
	global_load_dword v66, v32, s[4:5]
	s_add_u32 s4, s4, 0x6000
	s_addc_u32 s5, s5, 0
	global_load_dword v67, v32, s[4:5]
	s_add_u32 s4, s4, 0x6000
	s_addc_u32 s5, s5, 0
	global_load_dword v68, v32, s[4:5]
	s_add_u32 s4, s4, 0x6000
	s_addc_u32 s5, s5, 0
	global_load_dword v69, v32, s[4:5]
	s_add_u32 s4, s4, 0x6000
	s_addc_u32 s5, s5, 0
	global_load_dword v70, v32, s[4:5]
	s_add_u32 s4, s4, 0x6000
	s_addc_u32 s5, s5, 0
	global_load_dword v71, v32, s[4:5]
	s_add_u32 s4, s4, 0x6000
	s_addc_u32 s5, s5, 0
	global_load_dword v72, v32, s[4:5]
	s_add_u32 s4, s4, 0x6000
	s_addc_u32 s5, s5, 0
	global_load_dword v73, v32, s[4:5]
	s_add_u32 s4, s4, 0x6000
	s_addc_u32 s5, s5, 0
	global_load_dword v74, v32, s[4:5]
	s_add_u32 s4, s4, 0x6000
	s_addc_u32 s5, s5, 0
	global_load_dword v75, v32, s[4:5]
	s_add_u32 s4, s4, 0x6000
	s_addc_u32 s5, s5, 0
	global_load_dword v76, v32, s[4:5]
	s_add_u32 s4, s4, 0x6000
	s_addc_u32 s5, s5, 0
	global_load_dword v77, v32, s[4:5]
	s_add_u32 s4, s4, 0x6000
	s_addc_u32 s5, s5, 0
	global_load_dword v78, v32, s[4:5]
	s_add_u32 s4, s4, 0x6000
	s_addc_u32 s5, s5, 0
	global_load_dword v79, v32, s[4:5]
	s_add_u32 s4, s4, 0x6000
	s_addc_u32 s5, s5, 0
	global_load_dword v80, v32, s[4:5]
	s_add_u32 s4, s4, 0x6000
	s_addc_u32 s5, s5, 0
	global_load_dword v81, v32, s[4:5]
	s_add_u32 s4, s4, 0x6000
	s_addc_u32 s5, s5, 0
	global_load_dword v82, v32, s[4:5]
	s_add_u32 s4, s4, 0x6000
	s_addc_u32 s5, s5, 0
	global_load_dword v83, v32, s[4:5]
	s_add_u32 s4, s4, 0x6000
	s_addc_u32 s5, s5, 0
	global_load_dword v84, v32, s[4:5]
	s_add_u32 s4, s4, 0x6000
	s_addc_u32 s5, s5, 0
	global_load_dword v85, v32, s[4:5]
	s_add_u32 s4, s4, 0x6000
	s_addc_u32 s5, s5, 0
	global_load_dword v86, v32, s[4:5]
	s_add_u32 s4, s4, 0x6000
	s_addc_u32 s5, s5, 0
	global_load_dword v87, v32, s[4:5]
	s_add_u32 s4, s4, 0x6000
	s_addc_u32 s5, s5, 0
	global_load_dword v88, v32, s[4:5]
	s_add_u32 s4, s4, 0x6000
	s_addc_u32 s5, s5, 0
	global_load_dword v89, v32, s[4:5]
	s_add_u32 s4, s4, 0x6000
	s_addc_u32 s5, s5, 0
	global_load_dword v90, v32, s[4:5]
	s_add_u32 s4, s4, 0x6000
	s_addc_u32 s5, s5, 0
	global_load_dword v91, v32, s[4:5]
	s_add_u32 s4, s4, 0x6000
	s_addc_u32 s5, s5, 0
	global_load_dword v92, v32, s[4:5]
	s_add_u32 s4, s4, 0x6000
	s_addc_u32 s5, s5, 0
	global_load_dword v93, v32, s[4:5]
	s_add_u32 s4, s4, 0x6000
	s_addc_u32 s5, s5, 0
	s_mov_b32 s14, 0
.Linit_pass:
	s_waitcnt vmcnt(28)
	v_add_u32_e32 v109, 0x10000, v60
	ds_read_b128 v[2:5], v60
	ds_read_b128 v[6:9], v60 offset:4096
	ds_read_b128 v[10:13], v60 offset:8192
	ds_read_b128 v[14:17], v60 offset:12288
	ds_read_b128 v[18:21], v60 offset:16384
	ds_read_b128 v[22:25], v60 offset:20480
	ds_read_b128 v[26:29], v60 offset:24576
	ds_read_b128 v[94:97], v60 offset:28672
	ds_read_b128 v[98:101], v60 offset:32768
	s_waitcnt lgkmcnt(8)
	v_mul_f32_e32 v108, v3, v63
	v_fmac_f32_e32 v108, v2, v62
	v_fmac_f32_e32 v108, v4, v64
	v_fmac_f32_e32 v108, v5, v65
	v_add_f32_e32 v59, v59, v108
	s_waitcnt lgkmcnt(7)
	v_mul_f32_e32 v108, v7, v63
	v_fmac_f32_e32 v108, v6, v62
	v_fmac_f32_e32 v108, v8, v64
	v_fmac_f32_e32 v108, v9, v65
	v_add_f32_e32 v55, v55, v108
	s_waitcnt lgkmcnt(6)
	v_mul_f32_e32 v108, v11, v63
	v_fmac_f32_e32 v108, v10, v62
	v_fmac_f32_e32 v108, v12, v64
	v_fmac_f32_e32 v108, v13, v65
	v_add_f32_e32 v54, v54, v108
	s_waitcnt lgkmcnt(5)
	v_mul_f32_e32 v108, v15, v63
	v_fmac_f32_e32 v108, v14, v62
	v_fmac_f32_e32 v108, v16, v64
	v_fmac_f32_e32 v108, v17, v65
	v_add_f32_e32 v53, v53, v108
	s_waitcnt lgkmcnt(4)
	v_mul_f32_e32 v108, v19, v63
	v_fmac_f32_e32 v108, v18, v62
	v_fmac_f32_e32 v108, v20, v64
	v_fmac_f32_e32 v108, v21, v65
	v_add_f32_e32 v52, v52, v108
	s_waitcnt lgkmcnt(3)
	v_mul_f32_e32 v108, v23, v63
	v_fmac_f32_e32 v108, v22, v62
	v_fmac_f32_e32 v108, v24, v64
	v_fmac_f32_e32 v108, v25, v65
	v_add_f32_e32 v51, v51, v108
	s_waitcnt lgkmcnt(2)
	v_mul_f32_e32 v108, v27, v63
	v_fmac_f32_e32 v108, v26, v62
	v_fmac_f32_e32 v108, v28, v64
	v_fmac_f32_e32 v108, v29, v65
	v_add_f32_e32 v50, v50, v108
	s_waitcnt lgkmcnt(1)
	v_mul_f32_e32 v108, v95, v63
	v_fmac_f32_e32 v108, v94, v62
	v_fmac_f32_e32 v108, v96, v64
	v_fmac_f32_e32 v108, v97, v65
	v_add_f32_e32 v49, v49, v108
	s_waitcnt lgkmcnt(0)
	v_mul_f32_e32 v108, v99, v63
	v_fmac_f32_e32 v108, v98, v62
	v_fmac_f32_e32 v108, v100, v64
	v_fmac_f32_e32 v108, v101, v65
	v_add_f32_e32 v48, v48, v108
	ds_read_b128 v[2:5], v60 offset:36864
	ds_read_b128 v[6:9], v60 offset:40960
	ds_read_b128 v[10:13], v60 offset:45056
	ds_read_b128 v[14:17], v60 offset:49152
	ds_read_b128 v[18:21], v60 offset:53248
	ds_read_b128 v[22:25], v60 offset:57344
	ds_read_b128 v[26:29], v60 offset:61440
	ds_read_b128 v[94:97], v109
	s_waitcnt lgkmcnt(7)
	v_mul_f32_e32 v108, v3, v63
	v_fmac_f32_e32 v108, v2, v62
	v_fmac_f32_e32 v108, v4, v64
	v_fmac_f32_e32 v108, v5, v65
	v_add_f32_e32 v47, v47, v108
	s_waitcnt lgkmcnt(6)
	v_mul_f32_e32 v108, v7, v63
	v_fmac_f32_e32 v108, v6, v62
	v_fmac_f32_e32 v108, v8, v64
	v_fmac_f32_e32 v108, v9, v65
	v_add_f32_e32 v46, v46, v108
	s_waitcnt lgkmcnt(5)
	v_mul_f32_e32 v108, v11, v63
	v_fmac_f32_e32 v108, v10, v62
	v_fmac_f32_e32 v108, v12, v64
	v_fmac_f32_e32 v108, v13, v65
	v_add_f32_e32 v45, v45, v108
	s_waitcnt lgkmcnt(4)
; __device__ __forceinline__ void phase_init(const Params& P, unsigned char* lds) {
;     ...
;         for (int k = wave * 128; k < wave * 128 + 128; k += 4) {
;             const float w0 = W[(size_t)k * MODW], w1 = W[(size_t)(k + 1) * MODW], w2 = W[(size_t)(k + 2) * MODW], w3 = W[(size_t)(k + 3) * MODW];
; #pragma unroll
;             for (int bb = 0; bb < 17; ++bb) { const f32x4 s4 = *(const f32x4*)(sc + bb * DM + k); acc[bb] += s4.x * w0 + s4.y * w1 + s4.z * w2 + s4.w * w3; }
;         }
	v_mul_f32_e32 v108, v15, v63
	v_fmac_f32_e32 v108, v14, v62
	v_fmac_f32_e32 v108, v16, v64
	v_fmac_f32_e32 v108, v17, v65
	v_add_f32_e32 v44, v44, v108
	s_waitcnt lgkmcnt(3)
	v_mul_f32_e32 v108, v19, v63
	v_fmac_f32_e32 v108, v18, v62
	v_fmac_f32_e32 v108, v20, v64
	v_fmac_f32_e32 v108, v21, v65
	v_add_f32_e32 v41, v41, v108
	s_waitcnt lgkmcnt(2)
	v_mul_f32_e32 v108, v23, v63
	v_fmac_f32_e32 v108, v22, v62
	v_fmac_f32_e32 v108, v24, v64
	v_fmac_f32_e32 v108, v25, v65
	v_add_f32_e32 v40, v40, v108
	s_waitcnt lgkmcnt(1)
	v_mul_f32_e32 v108, v27, v63
	v_fmac_f32_e32 v108, v26, v62
	v_fmac_f32_e32 v108, v28, v64
	v_fmac_f32_e32 v108, v29, v65
	v_add_f32_e32 v39, v39, v108
	s_waitcnt lgkmcnt(0)
	v_mul_f32_e32 v108, v95, v63
	v_fmac_f32_e32 v108, v94, v62
	v_fmac_f32_e32 v108, v96, v64
	v_fmac_f32_e32 v108, v97, v65
	v_add_f32_e32 v38, v38, v108
	global_load_dword v62, v32, s[4:5]
	s_add_u32 s4, s4, 0x6000
	s_addc_u32 s5, s5, 0
	global_load_dword v63, v32, s[4:5]
	s_add_u32 s4, s4, 0x6000
	s_addc_u32 s5, s5, 0
	global_load_dword v64, v32, s[4:5]
	s_add_u32 s4, s4, 0x6000
	s_addc_u32 s5, s5, 0
	global_load_dword v65, v32, s[4:5]
	s_add_u32 s4, s4, 0x6000
	s_addc_u32 s5, s5, 0
	v_add_u32_e32 v60, 16, v60
	s_waitcnt vmcnt(28)
	v_add_u32_e32 v109, 0x10000, v60
	ds_read_b128 v[2:5], v60
	ds_read_b128 v[6:9], v60 offset:4096
	ds_read_b128 v[10:13], v60 offset:8192
	ds_read_b128 v[14:17], v60 offset:12288
	ds_read_b128 v[18:21], v60 offset:16384
	ds_read_b128 v[22:25], v60 offset:20480
	ds_read_b128 v[26:29], v60 offset:24576
	ds_read_b128 v[94:97], v60 offset:28672
	ds_read_b128 v[98:101], v60 offset:32768
	s_waitcnt lgkmcnt(8)
	v_mul_f32_e32 v108, v3, v67
	v_fmac_f32_e32 v108, v2, v66
	v_fmac_f32_e32 v108, v4, v68
	v_fmac_f32_e32 v108, v5, v69
	v_add_f32_e32 v59, v59, v108
	s_waitcnt lgkmcnt(7)
	v_mul_f32_e32 v108, v7, v67
	v_fmac_f32_e32 v108, v6, v66
	v_fmac_f32_e32 v108, v8, v68
	v_fmac_f32_e32 v108, v9, v69
	v_add_f32_e32 v55, v55, v108
	s_waitcnt lgkmcnt(6)
	v_mul_f32_e32 v108, v11, v67
	v_fmac_f32_e32 v108, v10, v66
	v_fmac_f32_e32 v108, v12, v68
	v_fmac_f32_e32 v108, v13, v69
	v_add_f32_e32 v54, v54, v108
	s_waitcnt lgkmcnt(5)
	v_mul_f32_e32 v108, v15, v67
	v_fmac_f32_e32 v108, v14, v66
	v_fmac_f32_e32 v108, v16, v68
	v_fmac_f32_e32 v108, v17, v69
	v_add_f32_e32 v53, v53, v108
	s_waitcnt lgkmcnt(4)
	v_mul_f32_e32 v108, v19, v67
	v_fmac_f32_e32 v108, v18, v66
	v_fmac_f32_e32 v108, v20, v68
	v_fmac_f32_e32 v108, v21, v69
	v_add_f32_e32 v52, v52, v108
	s_waitcnt lgkmcnt(3)
	v_mul_f32_e32 v108, v23, v67
	v_fmac_f32_e32 v108, v22, v66
	v_fmac_f32_e32 v108, v24, v68
	v_fmac_f32_e32 v108, v25, v69
	v_add_f32_e32 v51, v51, v108
	s_waitcnt lgkmcnt(2)
	v_mul_f32_e32 v108, v27, v67
	v_fmac_f32_e32 v108, v26, v66
	v_fmac_f32_e32 v108, v28, v68
	v_fmac_f32_e32 v108, v29, v69
	v_add_f32_e32 v50, v50, v108
	s_waitcnt lgkmcnt(1)
	v_mul_f32_e32 v108, v95, v67
	v_fmac_f32_e32 v108, v94, v66
	v_fmac_f32_e32 v108, v96, v68
	v_fmac_f32_e32 v108, v97, v69
	v_add_f32_e32 v49, v49, v108
	s_waitcnt lgkmcnt(0)
	v_mul_f32_e32 v108, v99, v67
	v_fmac_f32_e32 v108, v98, v66
	v_fmac_f32_e32 v108, v100, v68
	v_fmac_f32_e32 v108, v101, v69
	v_add_f32_e32 v48, v48, v108
	ds_read_b128 v[2:5], v60 offset:36864
	ds_read_b128 v[6:9], v60 offset:40960
	ds_read_b128 v[10:13], v60 offset:45056
	ds_read_b128 v[14:17], v60 offset:49152
	ds_read_b128 v[18:21], v60 offset:53248
	ds_read_b128 v[22:25], v60 offset:57344
	ds_read_b128 v[26:29], v60 offset:61440
	ds_read_b128 v[94:97], v109
	s_waitcnt lgkmcnt(7)
	v_mul_f32_e32 v108, v3, v67
	v_fmac_f32_e32 v108, v2, v66
	v_fmac_f32_e32 v108, v4, v68
	v_fmac_f32_e32 v108, v5, v69
	v_add_f32_e32 v47, v47, v108
	s_waitcnt lgkmcnt(6)
	v_mul_f32_e32 v108, v7, v67
	v_fmac_f32_e32 v108, v6, v66
	v_fmac_f32_e32 v108, v8, v68
	v_fmac_f32_e32 v108, v9, v69
	v_add_f32_e32 v46, v46, v108
	s_waitcnt lgkmcnt(5)
	v_mul_f32_e32 v108, v11, v67
	v_fmac_f32_e32 v108, v10, v66
	v_fmac_f32_e32 v108, v12, v68
	v_fmac_f32_e32 v108, v13, v69
	v_add_f32_e32 v45, v45, v108
	s_waitcnt lgkmcnt(4)
	v_mul_f32_e32 v108, v15, v67
	v_fmac_f32_e32 v108, v14, v66
	v_fmac_f32_e32 v108, v16, v68
	v_fmac_f32_e32 v108, v17, v69
	v_add_f32_e32 v44, v44, v108
	s_waitcnt lgkmcnt(3)
	v_mul_f32_e32 v108, v19, v67
	v_fmac_f32_e32 v108, v18, v66
	v_fmac_f32_e32 v108, v20, v68
	v_fmac_f32_e32 v108, v21, v69
	v_add_f32_e32 v41, v41, v108
	s_waitcnt lgkmcnt(2)
	v_mul_f32_e32 v108, v23, v67
	v_fmac_f32_e32 v108, v22, v66
	v_fmac_f32_e32 v108, v24, v68
	v_fmac_f32_e32 v108, v25, v69
	v_add_f32_e32 v40, v40, v108
	s_waitcnt lgkmcnt(1)
	v_mul_f32_e32 v108, v27, v67
	v_fmac_f32_e32 v108, v26, v66
	v_fmac_f32_e32 v108, v28, v68
	v_fmac_f32_e32 v108, v29, v69
	v_add_f32_e32 v39, v39, v108
	s_waitcnt lgkmcnt(0)
	v_mul_f32_e32 v108, v95, v67
	v_fmac_f32_e32 v108, v94, v66
	v_fmac_f32_e32 v108, v96, v68
	v_fmac_f32_e32 v108, v97, v69
	v_add_f32_e32 v38, v38, v108
	global_load_dword v66, v32, s[4:5]
	s_add_u32 s4, s4, 0x6000
	s_addc_u32 s5, s5, 0
	global_load_dword v67, v32, s[4:5]
	s_add_u32 s4, s4, 0x6000
	s_addc_u32 s5, s5, 0
	global_load_dword v68, v32, s[4:5]
	s_add_u32 s4, s4, 0x6000
	s_addc_u32 s5, s5, 0
	global_load_dword v69, v32, s[4:5]
	s_add_u32 s4, s4, 0x6000
	s_addc_u32 s5, s5, 0
	v_add_u32_e32 v60, 16, v60
	s_waitcnt vmcnt(28)
	v_add_u32_e32 v109, 0x10000, v60
	ds_read_b128 v[2:5], v60
	ds_read_b128 v[6:9], v60 offset:4096
	ds_read_b128 v[10:13], v60 offset:8192
	ds_read_b128 v[14:17], v60 offset:12288
	ds_read_b128 v[18:21], v60 offset:16384
	ds_read_b128 v[22:25], v60 offset:20480
	ds_read_b128 v[26:29], v60 offset:24576
	ds_read_b128 v[94:97], v60 offset:28672
	ds_read_b128 v[98:101], v60 offset:32768
	s_waitcnt lgkmcnt(8)
; __device__ __forceinline__ void phase_init(const Params& P, unsigned char* lds) {
;     ...
;         for (int k = wave * 128; k < wave * 128 + 128; k += 4) {
;             const float w0 = W[(size_t)k * MODW], w1 = W[(size_t)(k + 1) * MODW], w2 = W[(size_t)(k + 2) * MODW], w3 = W[(size_t)(k + 3) * MODW];
; #pragma unroll
;             for (int bb = 0; bb < 17; ++bb) { const f32x4 s4 = *(const f32x4*)(sc + bb * DM + k); acc[bb] += s4.x * w0 + s4.y * w1 + s4.z * w2 + s4.w * w3; }
;         }
	v_mul_f32_e32 v108, v3, v71
	v_fmac_f32_e32 v108, v2, v70
	v_fmac_f32_e32 v108, v4, v72
	v_fmac_f32_e32 v108, v5, v73
	v_add_f32_e32 v59, v59, v108
	s_waitcnt lgkmcnt(7)
	v_mul_f32_e32 v108, v7, v71
	v_fmac_f32_e32 v108, v6, v70
	v_fmac_f32_e32 v108, v8, v72
	v_fmac_f32_e32 v108, v9, v73
	v_add_f32_e32 v55, v55, v108
	s_waitcnt lgkmcnt(6)
	v_mul_f32_e32 v108, v11, v71
	v_fmac_f32_e32 v108, v10, v70
	v_fmac_f32_e32 v108, v12, v72
	v_fmac_f32_e32 v108, v13, v73
	v_add_f32_e32 v54, v54, v108
	s_waitcnt lgkmcnt(5)
	v_mul_f32_e32 v108, v15, v71
	v_fmac_f32_e32 v108, v14, v70
	v_fmac_f32_e32 v108, v16, v72
	v_fmac_f32_e32 v108, v17, v73
	v_add_f32_e32 v53, v53, v108
	s_waitcnt lgkmcnt(4)
	v_mul_f32_e32 v108, v19, v71
	v_fmac_f32_e32 v108, v18, v70
	v_fmac_f32_e32 v108, v20, v72
	v_fmac_f32_e32 v108, v21, v73
	v_add_f32_e32 v52, v52, v108
	s_waitcnt lgkmcnt(3)
	v_mul_f32_e32 v108, v23, v71
	v_fmac_f32_e32 v108, v22, v70
	v_fmac_f32_e32 v108, v24, v72
	v_fmac_f32_e32 v108, v25, v73
	v_add_f32_e32 v51, v51, v108
	s_waitcnt lgkmcnt(2)
	v_mul_f32_e32 v108, v27, v71
	v_fmac_f32_e32 v108, v26, v70
	v_fmac_f32_e32 v108, v28, v72
	v_fmac_f32_e32 v108, v29, v73
	v_add_f32_e32 v50, v50, v108
	s_waitcnt lgkmcnt(1)
	v_mul_f32_e32 v108, v95, v71
	v_fmac_f32_e32 v108, v94, v70
	v_fmac_f32_e32 v108, v96, v72
	v_fmac_f32_e32 v108, v97, v73
	v_add_f32_e32 v49, v49, v108
	s_waitcnt lgkmcnt(0)
	v_mul_f32_e32 v108, v99, v71
	v_fmac_f32_e32 v108, v98, v70
	v_fmac_f32_e32 v108, v100, v72
	v_fmac_f32_e32 v108, v101, v73
	v_add_f32_e32 v48, v48, v108
	ds_read_b128 v[2:5], v60 offset:36864
	ds_read_b128 v[6:9], v60 offset:40960
	ds_read_b128 v[10:13], v60 offset:45056
	ds_read_b128 v[14:17], v60 offset:49152
	ds_read_b128 v[18:21], v60 offset:53248
	ds_read_b128 v[22:25], v60 offset:57344
	ds_read_b128 v[26:29], v60 offset:61440
	ds_read_b128 v[94:97], v109
	s_waitcnt lgkmcnt(7)
	v_mul_f32_e32 v108, v3, v71
	v_fmac_f32_e32 v108, v2, v70
	v_fmac_f32_e32 v108, v4, v72
	v_fmac_f32_e32 v108, v5, v73
	v_add_f32_e32 v47, v47, v108
	s_waitcnt lgkmcnt(6)
	v_mul_f32_e32 v108, v7, v71
	v_fmac_f32_e32 v108, v6, v70
	v_fmac_f32_e32 v108, v8, v72
	v_fmac_f32_e32 v108, v9, v73
	v_add_f32_e32 v46, v46, v108
	s_waitcnt lgkmcnt(5)
	v_mul_f32_e32 v108, v11, v71
	v_fmac_f32_e32 v108, v10, v70
	v_fmac_f32_e32 v108, v12, v72
	v_fmac_f32_e32 v108, v13, v73
	v_add_f32_e32 v45, v45, v108
	s_waitcnt lgkmcnt(4)
	v_mul_f32_e32 v108, v15, v71
	v_fmac_f32_e32 v108, v14, v70
	v_fmac_f32_e32 v108, v16, v72
	v_fmac_f32_e32 v108, v17, v73
	v_add_f32_e32 v44, v44, v108
	s_waitcnt lgkmcnt(3)
	v_mul_f32_e32 v108, v19, v71
	v_fmac_f32_e32 v108, v18, v70
	v_fmac_f32_e32 v108, v20, v72
	v_fmac_f32_e32 v108, v21, v73
	v_add_f32_e32 v41, v41, v108
	s_waitcnt lgkmcnt(2)
	v_mul_f32_e32 v108, v23, v71
	v_fmac_f32_e32 v108, v22, v70
	v_fmac_f32_e32 v108, v24, v72
	v_fmac_f32_e32 v108, v25, v73
	v_add_f32_e32 v40, v40, v108
	s_waitcnt lgkmcnt(1)
	v_mul_f32_e32 v108, v27, v71
	v_fmac_f32_e32 v108, v26, v70
	v_fmac_f32_e32 v108, v28, v72
	v_fmac_f32_e32 v108, v29, v73
	v_add_f32_e32 v39, v39, v108
	s_waitcnt lgkmcnt(0)
	v_mul_f32_e32 v108, v95, v71
	v_fmac_f32_e32 v108, v94, v70
	v_fmac_f32_e32 v108, v96, v72
	v_fmac_f32_e32 v108, v97, v73
	v_add_f32_e32 v38, v38, v108
	global_load_dword v70, v32, s[4:5]
	s_add_u32 s4, s4, 0x6000
	s_addc_u32 s5, s5, 0
	global_load_dword v71, v32, s[4:5]
	s_add_u32 s4, s4, 0x6000
	s_addc_u32 s5, s5, 0
	global_load_dword v72, v32, s[4:5]
	s_add_u32 s4, s4, 0x6000
	s_addc_u32 s5, s5, 0
	global_load_dword v73, v32, s[4:5]
	s_add_u32 s4, s4, 0x6000
	s_addc_u32 s5, s5, 0
	v_add_u32_e32 v60, 16, v60
	s_waitcnt vmcnt(28)
	v_add_u32_e32 v109, 0x10000, v60
	ds_read_b128 v[2:5], v60
	ds_read_b128 v[6:9], v60 offset:4096
	ds_read_b128 v[10:13], v60 offset:8192
	ds_read_b128 v[14:17], v60 offset:12288
	ds_read_b128 v[18:21], v60 offset:16384
	ds_read_b128 v[22:25], v60 offset:20480
	ds_read_b128 v[26:29], v60 offset:24576
	ds_read_b128 v[94:97], v60 offset:28672
	ds_read_b128 v[98:101], v60 offset:32768
	s_waitcnt lgkmcnt(8)
	v_mul_f32_e32 v108, v3, v75
	v_fmac_f32_e32 v108, v2, v74
	v_fmac_f32_e32 v108, v4, v76
	v_fmac_f32_e32 v108, v5, v77
	v_add_f32_e32 v59, v59, v108
	s_waitcnt lgkmcnt(7)
	v_mul_f32_e32 v108, v7, v75
	v_fmac_f32_e32 v108, v6, v74
	v_fmac_f32_e32 v108, v8, v76
	v_fmac_f32_e32 v108, v9, v77
	v_add_f32_e32 v55, v55, v108
	s_waitcnt lgkmcnt(6)
	v_mul_f32_e32 v108, v11, v75
	v_fmac_f32_e32 v108, v10, v74
	v_fmac_f32_e32 v108, v12, v76
	v_fmac_f32_e32 v108, v13, v77
	v_add_f32_e32 v54, v54, v108
	s_waitcnt lgkmcnt(5)
	v_mul_f32_e32 v108, v15, v75
	v_fmac_f32_e32 v108, v14, v74
	v_fmac_f32_e32 v108, v16, v76
	v_fmac_f32_e32 v108, v17, v77
	v_add_f32_e32 v53, v53, v108
	s_waitcnt lgkmcnt(4)
	v_mul_f32_e32 v108, v19, v75
	v_fmac_f32_e32 v108, v18, v74
	v_fmac_f32_e32 v108, v20, v76
	v_fmac_f32_e32 v108, v21, v77
	v_add_f32_e32 v52, v52, v108
	s_waitcnt lgkmcnt(3)
	v_mul_f32_e32 v108, v23, v75
	v_fmac_f32_e32 v108, v22, v74
	v_fmac_f32_e32 v108, v24, v76
	v_fmac_f32_e32 v108, v25, v77
	v_add_f32_e32 v51, v51, v108
	s_waitcnt lgkmcnt(2)
	v_mul_f32_e32 v108, v27, v75
	v_fmac_f32_e32 v108, v26, v74
	v_fmac_f32_e32 v108, v28, v76
	v_fmac_f32_e32 v108, v29, v77
	v_add_f32_e32 v50, v50, v108
	s_waitcnt lgkmcnt(1)
	v_mul_f32_e32 v108, v95, v75
	v_fmac_f32_e32 v108, v94, v74
	v_fmac_f32_e32 v108, v96, v76
	v_fmac_f32_e32 v108, v97, v77
	v_add_f32_e32 v49, v49, v108
	s_waitcnt lgkmcnt(0)
; __device__ __forceinline__ void phase_init(const Params& P, unsigned char* lds) {
;     ...
;         for (int k = wave * 128; k < wave * 128 + 128; k += 4) {
;             const float w0 = W[(size_t)k * MODW], w1 = W[(size_t)(k + 1) * MODW], w2 = W[(size_t)(k + 2) * MODW], w3 = W[(size_t)(k + 3) * MODW];
; #pragma unroll
;             for (int bb = 0; bb < 17; ++bb) { const f32x4 s4 = *(const f32x4*)(sc + bb * DM + k); acc[bb] += s4.x * w0 + s4.y * w1 + s4.z * w2 + s4.w * w3; }
;         }
	v_mul_f32_e32 v108, v99, v75
	v_fmac_f32_e32 v108, v98, v74
	v_fmac_f32_e32 v108, v100, v76
	v_fmac_f32_e32 v108, v101, v77
	v_add_f32_e32 v48, v48, v108
	ds_read_b128 v[2:5], v60 offset:36864
	ds_read_b128 v[6:9], v60 offset:40960
	ds_read_b128 v[10:13], v60 offset:45056
	ds_read_b128 v[14:17], v60 offset:49152
	ds_read_b128 v[18:21], v60 offset:53248
	ds_read_b128 v[22:25], v60 offset:57344
	ds_read_b128 v[26:29], v60 offset:61440
	ds_read_b128 v[94:97], v109
	s_waitcnt lgkmcnt(7)
	v_mul_f32_e32 v108, v3, v75
	v_fmac_f32_e32 v108, v2, v74
	v_fmac_f32_e32 v108, v4, v76
	v_fmac_f32_e32 v108, v5, v77
	v_add_f32_e32 v47, v47, v108
	s_waitcnt lgkmcnt(6)
	v_mul_f32_e32 v108, v7, v75
	v_fmac_f32_e32 v108, v6, v74
	v_fmac_f32_e32 v108, v8, v76
	v_fmac_f32_e32 v108, v9, v77
	v_add_f32_e32 v46, v46, v108
	s_waitcnt lgkmcnt(5)
	v_mul_f32_e32 v108, v11, v75
	v_fmac_f32_e32 v108, v10, v74
	v_fmac_f32_e32 v108, v12, v76
	v_fmac_f32_e32 v108, v13, v77
	v_add_f32_e32 v45, v45, v108
	s_waitcnt lgkmcnt(4)
	v_mul_f32_e32 v108, v15, v75
	v_fmac_f32_e32 v108, v14, v74
	v_fmac_f32_e32 v108, v16, v76
	v_fmac_f32_e32 v108, v17, v77
	v_add_f32_e32 v44, v44, v108
	s_waitcnt lgkmcnt(3)
	v_mul_f32_e32 v108, v19, v75
	v_fmac_f32_e32 v108, v18, v74
	v_fmac_f32_e32 v108, v20, v76
	v_fmac_f32_e32 v108, v21, v77
	v_add_f32_e32 v41, v41, v108
	s_waitcnt lgkmcnt(2)
	v_mul_f32_e32 v108, v23, v75
	v_fmac_f32_e32 v108, v22, v74
	v_fmac_f32_e32 v108, v24, v76
	v_fmac_f32_e32 v108, v25, v77
	v_add_f32_e32 v40, v40, v108
	s_waitcnt lgkmcnt(1)
	v_mul_f32_e32 v108, v27, v75
	v_fmac_f32_e32 v108, v26, v74
	v_fmac_f32_e32 v108, v28, v76
	v_fmac_f32_e32 v108, v29, v77
	v_add_f32_e32 v39, v39, v108
	s_waitcnt lgkmcnt(0)
	v_mul_f32_e32 v108, v95, v75
	v_fmac_f32_e32 v108, v94, v74
	v_fmac_f32_e32 v108, v96, v76
	v_fmac_f32_e32 v108, v97, v77
	v_add_f32_e32 v38, v38, v108
	global_load_dword v74, v32, s[4:5]
	s_add_u32 s4, s4, 0x6000
	s_addc_u32 s5, s5, 0
	global_load_dword v75, v32, s[4:5]
	s_add_u32 s4, s4, 0x6000
	s_addc_u32 s5, s5, 0
	global_load_dword v76, v32, s[4:5]
	s_add_u32 s4, s4, 0x6000
	s_addc_u32 s5, s5, 0
	global_load_dword v77, v32, s[4:5]
	s_add_u32 s4, s4, 0x6000
	s_addc_u32 s5, s5, 0
	v_add_u32_e32 v60, 16, v60
	s_waitcnt vmcnt(28)
	v_add_u32_e32 v109, 0x10000, v60
	ds_read_b128 v[2:5], v60
	ds_read_b128 v[6:9], v60 offset:4096
	ds_read_b128 v[10:13], v60 offset:8192
	ds_read_b128 v[14:17], v60 offset:12288
	ds_read_b128 v[18:21], v60 offset:16384
	ds_read_b128 v[22:25], v60 offset:20480
	ds_read_b128 v[26:29], v60 offset:24576
	ds_read_b128 v[94:97], v60 offset:28672
	ds_read_b128 v[98:101], v60 offset:32768
	s_waitcnt lgkmcnt(8)
	v_mul_f32_e32 v108, v3, v79
	v_fmac_f32_e32 v108, v2, v78
	v_fmac_f32_e32 v108, v4, v80
	v_fmac_f32_e32 v108, v5, v81
	v_add_f32_e32 v59, v59, v108
	s_waitcnt lgkmcnt(7)
	v_mul_f32_e32 v108, v7, v79
	v_fmac_f32_e32 v108, v6, v78
	v_fmac_f32_e32 v108, v8, v80
	v_fmac_f32_e32 v108, v9, v81
	v_add_f32_e32 v55, v55, v108
	s_waitcnt lgkmcnt(6)
	v_mul_f32_e32 v108, v11, v79
	v_fmac_f32_e32 v108, v10, v78
	v_fmac_f32_e32 v108, v12, v80
	v_fmac_f32_e32 v108, v13, v81
	v_add_f32_e32 v54, v54, v108
	s_waitcnt lgkmcnt(5)
	v_mul_f32_e32 v108, v15, v79
	v_fmac_f32_e32 v108, v14, v78
	v_fmac_f32_e32 v108, v16, v80
	v_fmac_f32_e32 v108, v17, v81
	v_add_f32_e32 v53, v53, v108
	s_waitcnt lgkmcnt(4)
	v_mul_f32_e32 v108, v19, v79
	v_fmac_f32_e32 v108, v18, v78
	v_fmac_f32_e32 v108, v20, v80
	v_fmac_f32_e32 v108, v21, v81
	v_add_f32_e32 v52, v52, v108
	s_waitcnt lgkmcnt(3)
	v_mul_f32_e32 v108, v23, v79
	v_fmac_f32_e32 v108, v22, v78
	v_fmac_f32_e32 v108, v24, v80
	v_fmac_f32_e32 v108, v25, v81
	v_add_f32_e32 v51, v51, v108
	s_waitcnt lgkmcnt(2)
	v_mul_f32_e32 v108, v27, v79
	v_fmac_f32_e32 v108, v26, v78
	v_fmac_f32_e32 v108, v28, v80
	v_fmac_f32_e32 v108, v29, v81
	v_add_f32_e32 v50, v50, v108
	s_waitcnt lgkmcnt(1)
	v_mul_f32_e32 v108, v95, v79
	v_fmac_f32_e32 v108, v94, v78
	v_fmac_f32_e32 v108, v96, v80
	v_fmac_f32_e32 v108, v97, v81
	v_add_f32_e32 v49, v49, v108
	s_waitcnt lgkmcnt(0)
	v_mul_f32_e32 v108, v99, v79
	v_fmac_f32_e32 v108, v98, v78
	v_fmac_f32_e32 v108, v100, v80
	v_fmac_f32_e32 v108, v101, v81
	v_add_f32_e32 v48, v48, v108
	ds_read_b128 v[2:5], v60 offset:36864
	ds_read_b128 v[6:9], v60 offset:40960
	ds_read_b128 v[10:13], v60 offset:45056
	ds_read_b128 v[14:17], v60 offset:49152
	ds_read_b128 v[18:21], v60 offset:53248
	ds_read_b128 v[22:25], v60 offset:57344
	ds_read_b128 v[26:29], v60 offset:61440
	ds_read_b128 v[94:97], v109
	s_waitcnt lgkmcnt(7)
	v_mul_f32_e32 v108, v3, v79
	v_fmac_f32_e32 v108, v2, v78
	v_fmac_f32_e32 v108, v4, v80
	v_fmac_f32_e32 v108, v5, v81
	v_add_f32_e32 v47, v47, v108
	s_waitcnt lgkmcnt(6)
	v_mul_f32_e32 v108, v7, v79
	v_fmac_f32_e32 v108, v6, v78
	v_fmac_f32_e32 v108, v8, v80
	v_fmac_f32_e32 v108, v9, v81
	v_add_f32_e32 v46, v46, v108
	s_waitcnt lgkmcnt(5)
	v_mul_f32_e32 v108, v11, v79
	v_fmac_f32_e32 v108, v10, v78
	v_fmac_f32_e32 v108, v12, v80
	v_fmac_f32_e32 v108, v13, v81
	v_add_f32_e32 v45, v45, v108
	s_waitcnt lgkmcnt(4)
	v_mul_f32_e32 v108, v15, v79
	v_fmac_f32_e32 v108, v14, v78
	v_fmac_f32_e32 v108, v16, v80
	v_fmac_f32_e32 v108, v17, v81
	v_add_f32_e32 v44, v44, v108
	s_waitcnt lgkmcnt(3)
	v_mul_f32_e32 v108, v19, v79
	v_fmac_f32_e32 v108, v18, v78
	v_fmac_f32_e32 v108, v20, v80
	v_fmac_f32_e32 v108, v21, v81
	v_add_f32_e32 v41, v41, v108
	s_waitcnt lgkmcnt(2)
	v_mul_f32_e32 v108, v23, v79
	v_fmac_f32_e32 v108, v22, v78
	v_fmac_f32_e32 v108, v24, v80
	v_fmac_f32_e32 v108, v25, v81
	v_add_f32_e32 v40, v40, v108
	s_waitcnt lgkmcnt(1)
; __device__ __forceinline__ void phase_init(const Params& P, unsigned char* lds) {
;     ...
;         for (int k = wave * 128; k < wave * 128 + 128; k += 4) {
;             const float w0 = W[(size_t)k * MODW], w1 = W[(size_t)(k + 1) * MODW], w2 = W[(size_t)(k + 2) * MODW], w3 = W[(size_t)(k + 3) * MODW];
; #pragma unroll
;             for (int bb = 0; bb < 17; ++bb) { const f32x4 s4 = *(const f32x4*)(sc + bb * DM + k); acc[bb] += s4.x * w0 + s4.y * w1 + s4.z * w2 + s4.w * w3; }
;         }
	v_mul_f32_e32 v108, v27, v79
	v_fmac_f32_e32 v108, v26, v78
	v_fmac_f32_e32 v108, v28, v80
	v_fmac_f32_e32 v108, v29, v81
	v_add_f32_e32 v39, v39, v108
	s_waitcnt lgkmcnt(0)
	v_mul_f32_e32 v108, v95, v79
	v_fmac_f32_e32 v108, v94, v78
	v_fmac_f32_e32 v108, v96, v80
	v_fmac_f32_e32 v108, v97, v81
	v_add_f32_e32 v38, v38, v108
	global_load_dword v78, v32, s[4:5]
	s_add_u32 s4, s4, 0x6000
	s_addc_u32 s5, s5, 0
	global_load_dword v79, v32, s[4:5]
	s_add_u32 s4, s4, 0x6000
	s_addc_u32 s5, s5, 0
	global_load_dword v80, v32, s[4:5]
	s_add_u32 s4, s4, 0x6000
	s_addc_u32 s5, s5, 0
	global_load_dword v81, v32, s[4:5]
	s_add_u32 s4, s4, 0x6000
	s_addc_u32 s5, s5, 0
	v_add_u32_e32 v60, 16, v60
	s_waitcnt vmcnt(28)
	v_add_u32_e32 v109, 0x10000, v60
	ds_read_b128 v[2:5], v60
	ds_read_b128 v[6:9], v60 offset:4096
	ds_read_b128 v[10:13], v60 offset:8192
	ds_read_b128 v[14:17], v60 offset:12288
	ds_read_b128 v[18:21], v60 offset:16384
	ds_read_b128 v[22:25], v60 offset:20480
	ds_read_b128 v[26:29], v60 offset:24576
	ds_read_b128 v[94:97], v60 offset:28672
	ds_read_b128 v[98:101], v60 offset:32768
	s_waitcnt lgkmcnt(8)
	v_mul_f32_e32 v108, v3, v83
	v_fmac_f32_e32 v108, v2, v82
	v_fmac_f32_e32 v108, v4, v84
	v_fmac_f32_e32 v108, v5, v85
	v_add_f32_e32 v59, v59, v108
	s_waitcnt lgkmcnt(7)
	v_mul_f32_e32 v108, v7, v83
	v_fmac_f32_e32 v108, v6, v82
	v_fmac_f32_e32 v108, v8, v84
	v_fmac_f32_e32 v108, v9, v85
	v_add_f32_e32 v55, v55, v108
	s_waitcnt lgkmcnt(6)
	v_mul_f32_e32 v108, v11, v83
	v_fmac_f32_e32 v108, v10, v82
	v_fmac_f32_e32 v108, v12, v84
	v_fmac_f32_e32 v108, v13, v85
	v_add_f32_e32 v54, v54, v108
	s_waitcnt lgkmcnt(5)
	v_mul_f32_e32 v108, v15, v83
	v_fmac_f32_e32 v108, v14, v82
	v_fmac_f32_e32 v108, v16, v84
	v_fmac_f32_e32 v108, v17, v85
	v_add_f32_e32 v53, v53, v108
	s_waitcnt lgkmcnt(4)
	v_mul_f32_e32 v108, v19, v83
	v_fmac_f32_e32 v108, v18, v82
	v_fmac_f32_e32 v108, v20, v84
	v_fmac_f32_e32 v108, v21, v85
	v_add_f32_e32 v52, v52, v108
	s_waitcnt lgkmcnt(3)
	v_mul_f32_e32 v108, v23, v83
	v_fmac_f32_e32 v108, v22, v82
	v_fmac_f32_e32 v108, v24, v84
	v_fmac_f32_e32 v108, v25, v85
	v_add_f32_e32 v51, v51, v108
	s_waitcnt lgkmcnt(2)
	v_mul_f32_e32 v108, v27, v83
	v_fmac_f32_e32 v108, v26, v82
	v_fmac_f32_e32 v108, v28, v84
	v_fmac_f32_e32 v108, v29, v85
	v_add_f32_e32 v50, v50, v108
	s_waitcnt lgkmcnt(1)
	v_mul_f32_e32 v108, v95, v83
	v_fmac_f32_e32 v108, v94, v82
	v_fmac_f32_e32 v108, v96, v84
	v_fmac_f32_e32 v108, v97, v85
	v_add_f32_e32 v49, v49, v108
	s_waitcnt lgkmcnt(0)
	v_mul_f32_e32 v108, v99, v83
	v_fmac_f32_e32 v108, v98, v82
	v_fmac_f32_e32 v108, v100, v84
	v_fmac_f32_e32 v108, v101, v85
	v_add_f32_e32 v48, v48, v108
	ds_read_b128 v[2:5], v60 offset:36864
	ds_read_b128 v[6:9], v60 offset:40960
	ds_read_b128 v[10:13], v60 offset:45056
	ds_read_b128 v[14:17], v60 offset:49152
	ds_read_b128 v[18:21], v60 offset:53248
	ds_read_b128 v[22:25], v60 offset:57344
	ds_read_b128 v[26:29], v60 offset:61440
	ds_read_b128 v[94:97], v109
	s_waitcnt lgkmcnt(7)
	v_mul_f32_e32 v108, v3, v83
	v_fmac_f32_e32 v108, v2, v82
	v_fmac_f32_e32 v108, v4, v84
	v_fmac_f32_e32 v108, v5, v85
	v_add_f32_e32 v47, v47, v108
	s_waitcnt lgkmcnt(6)
	v_mul_f32_e32 v108, v7, v83
	v_fmac_f32_e32 v108, v6, v82
	v_fmac_f32_e32 v108, v8, v84
	v_fmac_f32_e32 v108, v9, v85
	v_add_f32_e32 v46, v46, v108
	s_waitcnt lgkmcnt(5)
	v_mul_f32_e32 v108, v11, v83
	v_fmac_f32_e32 v108, v10, v82
	v_fmac_f32_e32 v108, v12, v84
	v_fmac_f32_e32 v108, v13, v85
	v_add_f32_e32 v45, v45, v108
	s_waitcnt lgkmcnt(4)
	v_mul_f32_e32 v108, v15, v83
	v_fmac_f32_e32 v108, v14, v82
	v_fmac_f32_e32 v108, v16, v84
	v_fmac_f32_e32 v108, v17, v85
	v_add_f32_e32 v44, v44, v108
	s_waitcnt lgkmcnt(3)
	v_mul_f32_e32 v108, v19, v83
	v_fmac_f32_e32 v108, v18, v82
	v_fmac_f32_e32 v108, v20, v84
	v_fmac_f32_e32 v108, v21, v85
	v_add_f32_e32 v41, v41, v108
	s_waitcnt lgkmcnt(2)
	v_mul_f32_e32 v108, v23, v83
	v_fmac_f32_e32 v108, v22, v82
	v_fmac_f32_e32 v108, v24, v84
	v_fmac_f32_e32 v108, v25, v85
	v_add_f32_e32 v40, v40, v108
	s_waitcnt lgkmcnt(1)
	v_mul_f32_e32 v108, v27, v83
	v_fmac_f32_e32 v108, v26, v82
	v_fmac_f32_e32 v108, v28, v84
	v_fmac_f32_e32 v108, v29, v85
	v_add_f32_e32 v39, v39, v108
	s_waitcnt lgkmcnt(0)
	v_mul_f32_e32 v108, v95, v83
	v_fmac_f32_e32 v108, v94, v82
	v_fmac_f32_e32 v108, v96, v84
	v_fmac_f32_e32 v108, v97, v85
	v_add_f32_e32 v38, v38, v108
	global_load_dword v82, v32, s[4:5]
	s_add_u32 s4, s4, 0x6000
	s_addc_u32 s5, s5, 0
	global_load_dword v83, v32, s[4:5]
	s_add_u32 s4, s4, 0x6000
	s_addc_u32 s5, s5, 0
	global_load_dword v84, v32, s[4:5]
	s_add_u32 s4, s4, 0x6000
	s_addc_u32 s5, s5, 0
	global_load_dword v85, v32, s[4:5]
	s_add_u32 s4, s4, 0x6000
	s_addc_u32 s5, s5, 0
	v_add_u32_e32 v60, 16, v60
	s_waitcnt vmcnt(28)
	v_add_u32_e32 v109, 0x10000, v60
	ds_read_b128 v[2:5], v60
	ds_read_b128 v[6:9], v60 offset:4096
	ds_read_b128 v[10:13], v60 offset:8192
	ds_read_b128 v[14:17], v60 offset:12288
	ds_read_b128 v[18:21], v60 offset:16384
	ds_read_b128 v[22:25], v60 offset:20480
	ds_read_b128 v[26:29], v60 offset:24576
	ds_read_b128 v[94:97], v60 offset:28672
	ds_read_b128 v[98:101], v60 offset:32768
	s_waitcnt lgkmcnt(8)
	v_mul_f32_e32 v108, v3, v87
	v_fmac_f32_e32 v108, v2, v86
	v_fmac_f32_e32 v108, v4, v88
	v_fmac_f32_e32 v108, v5, v89
	v_add_f32_e32 v59, v59, v108
	s_waitcnt lgkmcnt(7)
	v_mul_f32_e32 v108, v7, v87
	v_fmac_f32_e32 v108, v6, v86
	v_fmac_f32_e32 v108, v8, v88
	v_fmac_f32_e32 v108, v9, v89
	v_add_f32_e32 v55, v55, v108
	s_waitcnt lgkmcnt(6)
	v_mul_f32_e32 v108, v11, v87
	v_fmac_f32_e32 v108, v10, v86
	v_fmac_f32_e32 v108, v12, v88
	v_fmac_f32_e32 v108, v13, v89
	v_add_f32_e32 v54, v54, v108
	s_waitcnt lgkmcnt(5)
; __device__ __forceinline__ void phase_init(const Params& P, unsigned char* lds) {
;     ...
;         for (int k = wave * 128; k < wave * 128 + 128; k += 4) {
;             const float w0 = W[(size_t)k * MODW], w1 = W[(size_t)(k + 1) * MODW], w2 = W[(size_t)(k + 2) * MODW], w3 = W[(size_t)(k + 3) * MODW];
; #pragma unroll
;             for (int bb = 0; bb < 17; ++bb) { const f32x4 s4 = *(const f32x4*)(sc + bb * DM + k); acc[bb] += s4.x * w0 + s4.y * w1 + s4.z * w2 + s4.w * w3; }
;         }
	v_mul_f32_e32 v108, v15, v87
	v_fmac_f32_e32 v108, v14, v86
	v_fmac_f32_e32 v108, v16, v88
	v_fmac_f32_e32 v108, v17, v89
	v_add_f32_e32 v53, v53, v108
	s_waitcnt lgkmcnt(4)
	v_mul_f32_e32 v108, v19, v87
	v_fmac_f32_e32 v108, v18, v86
	v_fmac_f32_e32 v108, v20, v88
	v_fmac_f32_e32 v108, v21, v89
	v_add_f32_e32 v52, v52, v108
	s_waitcnt lgkmcnt(3)
	v_mul_f32_e32 v108, v23, v87
	v_fmac_f32_e32 v108, v22, v86
	v_fmac_f32_e32 v108, v24, v88
	v_fmac_f32_e32 v108, v25, v89
	v_add_f32_e32 v51, v51, v108
	s_waitcnt lgkmcnt(2)
	v_mul_f32_e32 v108, v27, v87
	v_fmac_f32_e32 v108, v26, v86
	v_fmac_f32_e32 v108, v28, v88
	v_fmac_f32_e32 v108, v29, v89
	v_add_f32_e32 v50, v50, v108
	s_waitcnt lgkmcnt(1)
	v_mul_f32_e32 v108, v95, v87
	v_fmac_f32_e32 v108, v94, v86
	v_fmac_f32_e32 v108, v96, v88
	v_fmac_f32_e32 v108, v97, v89
	v_add_f32_e32 v49, v49, v108
	s_waitcnt lgkmcnt(0)
	v_mul_f32_e32 v108, v99, v87
	v_fmac_f32_e32 v108, v98, v86
	v_fmac_f32_e32 v108, v100, v88
	v_fmac_f32_e32 v108, v101, v89
	v_add_f32_e32 v48, v48, v108
	ds_read_b128 v[2:5], v60 offset:36864
	ds_read_b128 v[6:9], v60 offset:40960
	ds_read_b128 v[10:13], v60 offset:45056
	ds_read_b128 v[14:17], v60 offset:49152
	ds_read_b128 v[18:21], v60 offset:53248
	ds_read_b128 v[22:25], v60 offset:57344
	ds_read_b128 v[26:29], v60 offset:61440
	ds_read_b128 v[94:97], v109
	s_waitcnt lgkmcnt(7)
	v_mul_f32_e32 v108, v3, v87
	v_fmac_f32_e32 v108, v2, v86
	v_fmac_f32_e32 v108, v4, v88
	v_fmac_f32_e32 v108, v5, v89
	v_add_f32_e32 v47, v47, v108
	s_waitcnt lgkmcnt(6)
	v_mul_f32_e32 v108, v7, v87
	v_fmac_f32_e32 v108, v6, v86
	v_fmac_f32_e32 v108, v8, v88
	v_fmac_f32_e32 v108, v9, v89
	v_add_f32_e32 v46, v46, v108
	s_waitcnt lgkmcnt(5)
	v_mul_f32_e32 v108, v11, v87
	v_fmac_f32_e32 v108, v10, v86
	v_fmac_f32_e32 v108, v12, v88
	v_fmac_f32_e32 v108, v13, v89
	v_add_f32_e32 v45, v45, v108
	s_waitcnt lgkmcnt(4)
	v_mul_f32_e32 v108, v15, v87
	v_fmac_f32_e32 v108, v14, v86
	v_fmac_f32_e32 v108, v16, v88
	v_fmac_f32_e32 v108, v17, v89
	v_add_f32_e32 v44, v44, v108
	s_waitcnt lgkmcnt(3)
	v_mul_f32_e32 v108, v19, v87
	v_fmac_f32_e32 v108, v18, v86
	v_fmac_f32_e32 v108, v20, v88
	v_fmac_f32_e32 v108, v21, v89
	v_add_f32_e32 v41, v41, v108
	s_waitcnt lgkmcnt(2)
	v_mul_f32_e32 v108, v23, v87
	v_fmac_f32_e32 v108, v22, v86
	v_fmac_f32_e32 v108, v24, v88
	v_fmac_f32_e32 v108, v25, v89
	v_add_f32_e32 v40, v40, v108
	s_waitcnt lgkmcnt(1)
	v_mul_f32_e32 v108, v27, v87
	v_fmac_f32_e32 v108, v26, v86
	v_fmac_f32_e32 v108, v28, v88
	v_fmac_f32_e32 v108, v29, v89
	v_add_f32_e32 v39, v39, v108
	s_waitcnt lgkmcnt(0)
	v_mul_f32_e32 v108, v95, v87
	v_fmac_f32_e32 v108, v94, v86
	v_fmac_f32_e32 v108, v96, v88
	v_fmac_f32_e32 v108, v97, v89
	v_add_f32_e32 v38, v38, v108
	global_load_dword v86, v32, s[4:5]
	s_add_u32 s4, s4, 0x6000
	s_addc_u32 s5, s5, 0
	global_load_dword v87, v32, s[4:5]
	s_add_u32 s4, s4, 0x6000
	s_addc_u32 s5, s5, 0
	global_load_dword v88, v32, s[4:5]
	s_add_u32 s4, s4, 0x6000
	s_addc_u32 s5, s5, 0
	global_load_dword v89, v32, s[4:5]
	s_add_u32 s4, s4, 0x6000
	s_addc_u32 s5, s5, 0
	v_add_u32_e32 v60, 16, v60
	s_waitcnt vmcnt(28)
	v_add_u32_e32 v109, 0x10000, v60
	ds_read_b128 v[2:5], v60
	ds_read_b128 v[6:9], v60 offset:4096
	ds_read_b128 v[10:13], v60 offset:8192
	ds_read_b128 v[14:17], v60 offset:12288
	ds_read_b128 v[18:21], v60 offset:16384
	ds_read_b128 v[22:25], v60 offset:20480
	ds_read_b128 v[26:29], v60 offset:24576
	ds_read_b128 v[94:97], v60 offset:28672
	ds_read_b128 v[98:101], v60 offset:32768
	s_waitcnt lgkmcnt(8)
	v_mul_f32_e32 v108, v3, v91
	v_fmac_f32_e32 v108, v2, v90
	v_fmac_f32_e32 v108, v4, v92
	v_fmac_f32_e32 v108, v5, v93
	v_add_f32_e32 v59, v59, v108
	s_waitcnt lgkmcnt(7)
	v_mul_f32_e32 v108, v7, v91
	v_fmac_f32_e32 v108, v6, v90
	v_fmac_f32_e32 v108, v8, v92
	v_fmac_f32_e32 v108, v9, v93
	v_add_f32_e32 v55, v55, v108
	s_waitcnt lgkmcnt(6)
	v_mul_f32_e32 v108, v11, v91
	v_fmac_f32_e32 v108, v10, v90
	v_fmac_f32_e32 v108, v12, v92
	v_fmac_f32_e32 v108, v13, v93
	v_add_f32_e32 v54, v54, v108
	s_waitcnt lgkmcnt(5)
	v_mul_f32_e32 v108, v15, v91
	v_fmac_f32_e32 v108, v14, v90
	v_fmac_f32_e32 v108, v16, v92
	v_fmac_f32_e32 v108, v17, v93
	v_add_f32_e32 v53, v53, v108
	s_waitcnt lgkmcnt(4)
	v_mul_f32_e32 v108, v19, v91
	v_fmac_f32_e32 v108, v18, v90
	v_fmac_f32_e32 v108, v20, v92
	v_fmac_f32_e32 v108, v21, v93
	v_add_f32_e32 v52, v52, v108
	s_waitcnt lgkmcnt(3)
	v_mul_f32_e32 v108, v23, v91
	v_fmac_f32_e32 v108, v22, v90
	v_fmac_f32_e32 v108, v24, v92
	v_fmac_f32_e32 v108, v25, v93
	v_add_f32_e32 v51, v51, v108
	s_waitcnt lgkmcnt(2)
	v_mul_f32_e32 v108, v27, v91
	v_fmac_f32_e32 v108, v26, v90
	v_fmac_f32_e32 v108, v28, v92
	v_fmac_f32_e32 v108, v29, v93
	v_add_f32_e32 v50, v50, v108
	s_waitcnt lgkmcnt(1)
	v_mul_f32_e32 v108, v95, v91
	v_fmac_f32_e32 v108, v94, v90
	v_fmac_f32_e32 v108, v96, v92
	v_fmac_f32_e32 v108, v97, v93
	v_add_f32_e32 v49, v49, v108
	s_waitcnt lgkmcnt(0)
	v_mul_f32_e32 v108, v99, v91
	v_fmac_f32_e32 v108, v98, v90
	v_fmac_f32_e32 v108, v100, v92
	v_fmac_f32_e32 v108, v101, v93
	v_add_f32_e32 v48, v48, v108
	ds_read_b128 v[2:5], v60 offset:36864
	ds_read_b128 v[6:9], v60 offset:40960
	ds_read_b128 v[10:13], v60 offset:45056
	ds_read_b128 v[14:17], v60 offset:49152
	ds_read_b128 v[18:21], v60 offset:53248
	ds_read_b128 v[22:25], v60 offset:57344
	ds_read_b128 v[26:29], v60 offset:61440
	ds_read_b128 v[94:97], v109
	s_waitcnt lgkmcnt(7)
	v_mul_f32_e32 v108, v3, v91
	v_fmac_f32_e32 v108, v2, v90
	v_fmac_f32_e32 v108, v4, v92
	v_fmac_f32_e32 v108, v5, v93
	v_add_f32_e32 v47, v47, v108
	s_waitcnt lgkmcnt(6)
; __device__ __forceinline__ void phase_init(const Params& P, unsigned char* lds) {
;     ...
;         for (int k = wave * 128; k < wave * 128 + 128; k += 4) {
;             const float w0 = W[(size_t)k * MODW], w1 = W[(size_t)(k + 1) * MODW], w2 = W[(size_t)(k + 2) * MODW], w3 = W[(size_t)(k + 3) * MODW];
; #pragma unroll
;             for (int bb = 0; bb < 17; ++bb) { const f32x4 s4 = *(const f32x4*)(sc + bb * DM + k); acc[bb] += s4.x * w0 + s4.y * w1 + s4.z * w2 + s4.w * w3; }
;         }
	v_mul_f32_e32 v108, v7, v91
	v_fmac_f32_e32 v108, v6, v90
	v_fmac_f32_e32 v108, v8, v92
	v_fmac_f32_e32 v108, v9, v93
	v_add_f32_e32 v46, v46, v108
	s_waitcnt lgkmcnt(5)
	v_mul_f32_e32 v108, v11, v91
	v_fmac_f32_e32 v108, v10, v90
	v_fmac_f32_e32 v108, v12, v92
	v_fmac_f32_e32 v108, v13, v93
	v_add_f32_e32 v45, v45, v108
	s_waitcnt lgkmcnt(4)
	v_mul_f32_e32 v108, v15, v91
	v_fmac_f32_e32 v108, v14, v90
	v_fmac_f32_e32 v108, v16, v92
	v_fmac_f32_e32 v108, v17, v93
	v_add_f32_e32 v44, v44, v108
	s_waitcnt lgkmcnt(3)
	v_mul_f32_e32 v108, v19, v91
	v_fmac_f32_e32 v108, v18, v90
	v_fmac_f32_e32 v108, v20, v92
	v_fmac_f32_e32 v108, v21, v93
	v_add_f32_e32 v41, v41, v108
	s_waitcnt lgkmcnt(2)
	v_mul_f32_e32 v108, v23, v91
	v_fmac_f32_e32 v108, v22, v90
	v_fmac_f32_e32 v108, v24, v92
	v_fmac_f32_e32 v108, v25, v93
	v_add_f32_e32 v40, v40, v108
	s_waitcnt lgkmcnt(1)
	v_mul_f32_e32 v108, v27, v91
	v_fmac_f32_e32 v108, v26, v90
	v_fmac_f32_e32 v108, v28, v92
	v_fmac_f32_e32 v108, v29, v93
	v_add_f32_e32 v39, v39, v108
	s_waitcnt lgkmcnt(0)
	v_mul_f32_e32 v108, v95, v91
	v_fmac_f32_e32 v108, v94, v90
	v_fmac_f32_e32 v108, v96, v92
	v_fmac_f32_e32 v108, v97, v93
	v_add_f32_e32 v38, v38, v108
	global_load_dword v90, v32, s[4:5]
	s_add_u32 s4, s4, 0x6000
	s_addc_u32 s5, s5, 0
	global_load_dword v91, v32, s[4:5]
	s_add_u32 s4, s4, 0x6000
	s_addc_u32 s5, s5, 0
	global_load_dword v92, v32, s[4:5]
	s_add_u32 s4, s4, 0x6000
	s_addc_u32 s5, s5, 0
	global_load_dword v93, v32, s[4:5]
	s_add_u32 s4, s4, 0x6000
	s_addc_u32 s5, s5, 0
	v_add_u32_e32 v60, 16, v60
	s_add_u32 s14, s14, 1
	s_cmp_lt_u32 s14, 3
	s_cbranch_scc1 .Linit_pass
	s_waitcnt vmcnt(28)
	v_add_u32_e32 v109, 0x10000, v60
	ds_read_b128 v[2:5], v60
	ds_read_b128 v[6:9], v60 offset:4096
	ds_read_b128 v[10:13], v60 offset:8192
	ds_read_b128 v[14:17], v60 offset:12288
	ds_read_b128 v[18:21], v60 offset:16384
	ds_read_b128 v[22:25], v60 offset:20480
	ds_read_b128 v[26:29], v60 offset:24576
	ds_read_b128 v[94:97], v60 offset:28672
	ds_read_b128 v[98:101], v60 offset:32768
	s_waitcnt lgkmcnt(8)
	v_mul_f32_e32 v108, v3, v63
	v_fmac_f32_e32 v108, v2, v62
	v_fmac_f32_e32 v108, v4, v64
	v_fmac_f32_e32 v108, v5, v65
	v_add_f32_e32 v59, v59, v108
	s_waitcnt lgkmcnt(7)
	v_mul_f32_e32 v108, v7, v63
	v_fmac_f32_e32 v108, v6, v62
	v_fmac_f32_e32 v108, v8, v64
	v_fmac_f32_e32 v108, v9, v65
	v_add_f32_e32 v55, v55, v108
	s_waitcnt lgkmcnt(6)
	v_mul_f32_e32 v108, v11, v63
	v_fmac_f32_e32 v108, v10, v62
	v_fmac_f32_e32 v108, v12, v64
	v_fmac_f32_e32 v108, v13, v65
	v_add_f32_e32 v54, v54, v108
	s_waitcnt lgkmcnt(5)
	v_mul_f32_e32 v108, v15, v63
	v_fmac_f32_e32 v108, v14, v62
	v_fmac_f32_e32 v108, v16, v64
	v_fmac_f32_e32 v108, v17, v65
	v_add_f32_e32 v53, v53, v108
	s_waitcnt lgkmcnt(4)
	v_mul_f32_e32 v108, v19, v63
	v_fmac_f32_e32 v108, v18, v62
	v_fmac_f32_e32 v108, v20, v64
	v_fmac_f32_e32 v108, v21, v65
	v_add_f32_e32 v52, v52, v108
	s_waitcnt lgkmcnt(3)
	v_mul_f32_e32 v108, v23, v63
	v_fmac_f32_e32 v108, v22, v62
	v_fmac_f32_e32 v108, v24, v64
	v_fmac_f32_e32 v108, v25, v65
	v_add_f32_e32 v51, v51, v108
	s_waitcnt lgkmcnt(2)
	v_mul_f32_e32 v108, v27, v63
	v_fmac_f32_e32 v108, v26, v62
	v_fmac_f32_e32 v108, v28, v64
	v_fmac_f32_e32 v108, v29, v65
	v_add_f32_e32 v50, v50, v108
	s_waitcnt lgkmcnt(1)
	v_mul_f32_e32 v108, v95, v63
	v_fmac_f32_e32 v108, v94, v62
	v_fmac_f32_e32 v108, v96, v64
	v_fmac_f32_e32 v108, v97, v65
	v_add_f32_e32 v49, v49, v108
	s_waitcnt lgkmcnt(0)
	v_mul_f32_e32 v108, v99, v63
	v_fmac_f32_e32 v108, v98, v62
	v_fmac_f32_e32 v108, v100, v64
	v_fmac_f32_e32 v108, v101, v65
	v_add_f32_e32 v48, v48, v108
	ds_read_b128 v[2:5], v60 offset:36864
	ds_read_b128 v[6:9], v60 offset:40960
	ds_read_b128 v[10:13], v60 offset:45056
	ds_read_b128 v[14:17], v60 offset:49152
	ds_read_b128 v[18:21], v60 offset:53248
	ds_read_b128 v[22:25], v60 offset:57344
	ds_read_b128 v[26:29], v60 offset:61440
	ds_read_b128 v[94:97], v109
	s_waitcnt lgkmcnt(7)
	v_mul_f32_e32 v108, v3, v63
	v_fmac_f32_e32 v108, v2, v62
	v_fmac_f32_e32 v108, v4, v64
	v_fmac_f32_e32 v108, v5, v65
	v_add_f32_e32 v47, v47, v108
	s_waitcnt lgkmcnt(6)
	v_mul_f32_e32 v108, v7, v63
	v_fmac_f32_e32 v108, v6, v62
	v_fmac_f32_e32 v108, v8, v64
	v_fmac_f32_e32 v108, v9, v65
	v_add_f32_e32 v46, v46, v108
	s_waitcnt lgkmcnt(5)
	v_mul_f32_e32 v108, v11, v63
	v_fmac_f32_e32 v108, v10, v62
	v_fmac_f32_e32 v108, v12, v64
	v_fmac_f32_e32 v108, v13, v65
	v_add_f32_e32 v45, v45, v108
	s_waitcnt lgkmcnt(4)
	v_mul_f32_e32 v108, v15, v63
	v_fmac_f32_e32 v108, v14, v62
	v_fmac_f32_e32 v108, v16, v64
	v_fmac_f32_e32 v108, v17, v65
	v_add_f32_e32 v44, v44, v108
	s_waitcnt lgkmcnt(3)
	v_mul_f32_e32 v108, v19, v63
	v_fmac_f32_e32 v108, v18, v62
	v_fmac_f32_e32 v108, v20, v64
	v_fmac_f32_e32 v108, v21, v65
	v_add_f32_e32 v41, v41, v108
	s_waitcnt lgkmcnt(2)
	v_mul_f32_e32 v108, v23, v63
	v_fmac_f32_e32 v108, v22, v62
	v_fmac_f32_e32 v108, v24, v64
	v_fmac_f32_e32 v108, v25, v65
	v_add_f32_e32 v40, v40, v108
	s_waitcnt lgkmcnt(1)
	v_mul_f32_e32 v108, v27, v63
	v_fmac_f32_e32 v108, v26, v62
	v_fmac_f32_e32 v108, v28, v64
	v_fmac_f32_e32 v108, v29, v65
	v_add_f32_e32 v39, v39, v108
	s_waitcnt lgkmcnt(0)
	v_mul_f32_e32 v108, v95, v63
	v_fmac_f32_e32 v108, v94, v62
	v_fmac_f32_e32 v108, v96, v64
	v_fmac_f32_e32 v108, v97, v65
	v_add_f32_e32 v38, v38, v108
	v_add_u32_e32 v60, 16, v60
	s_waitcnt vmcnt(24)
	v_add_u32_e32 v109, 0x10000, v60
	ds_read_b128 v[2:5], v60
	ds_read_b128 v[6:9], v60 offset:4096
	ds_read_b128 v[10:13], v60 offset:8192
	ds_read_b128 v[14:17], v60 offset:12288
	ds_read_b128 v[18:21], v60 offset:16384
	ds_read_b128 v[22:25], v60 offset:20480
	ds_read_b128 v[26:29], v60 offset:24576
	ds_read_b128 v[94:97], v60 offset:28672
	ds_read_b128 v[98:101], v60 offset:32768
	s_waitcnt lgkmcnt(8)
; __device__ __forceinline__ void phase_init(const Params& P, unsigned char* lds) {
;     ...
;         for (int k = wave * 128; k < wave * 128 + 128; k += 4) {
;             const float w0 = W[(size_t)k * MODW], w1 = W[(size_t)(k + 1) * MODW], w2 = W[(size_t)(k + 2) * MODW], w3 = W[(size_t)(k + 3) * MODW];
; #pragma unroll
;             for (int bb = 0; bb < 17; ++bb) { const f32x4 s4 = *(const f32x4*)(sc + bb * DM + k); acc[bb] += s4.x * w0 + s4.y * w1 + s4.z * w2 + s4.w * w3; }
;         }
	v_mul_f32_e32 v108, v3, v67
	v_fmac_f32_e32 v108, v2, v66
	v_fmac_f32_e32 v108, v4, v68
	v_fmac_f32_e32 v108, v5, v69
	v_add_f32_e32 v59, v59, v108
	s_waitcnt lgkmcnt(7)
	v_mul_f32_e32 v108, v7, v67
	v_fmac_f32_e32 v108, v6, v66
	v_fmac_f32_e32 v108, v8, v68
	v_fmac_f32_e32 v108, v9, v69
	v_add_f32_e32 v55, v55, v108
	s_waitcnt lgkmcnt(6)
	v_mul_f32_e32 v108, v11, v67
	v_fmac_f32_e32 v108, v10, v66
	v_fmac_f32_e32 v108, v12, v68
	v_fmac_f32_e32 v108, v13, v69
	v_add_f32_e32 v54, v54, v108
	s_waitcnt lgkmcnt(5)
	v_mul_f32_e32 v108, v15, v67
	v_fmac_f32_e32 v108, v14, v66
	v_fmac_f32_e32 v108, v16, v68
	v_fmac_f32_e32 v108, v17, v69
	v_add_f32_e32 v53, v53, v108
	s_waitcnt lgkmcnt(4)
	v_mul_f32_e32 v108, v19, v67
	v_fmac_f32_e32 v108, v18, v66
	v_fmac_f32_e32 v108, v20, v68
	v_fmac_f32_e32 v108, v21, v69
	v_add_f32_e32 v52, v52, v108
	s_waitcnt lgkmcnt(3)
	v_mul_f32_e32 v108, v23, v67
	v_fmac_f32_e32 v108, v22, v66
	v_fmac_f32_e32 v108, v24, v68
	v_fmac_f32_e32 v108, v25, v69
	v_add_f32_e32 v51, v51, v108
	s_waitcnt lgkmcnt(2)
	v_mul_f32_e32 v108, v27, v67
	v_fmac_f32_e32 v108, v26, v66
	v_fmac_f32_e32 v108, v28, v68
	v_fmac_f32_e32 v108, v29, v69
	v_add_f32_e32 v50, v50, v108
	s_waitcnt lgkmcnt(1)
	v_mul_f32_e32 v108, v95, v67
	v_fmac_f32_e32 v108, v94, v66
	v_fmac_f32_e32 v108, v96, v68
	v_fmac_f32_e32 v108, v97, v69
	v_add_f32_e32 v49, v49, v108
	s_waitcnt lgkmcnt(0)
	v_mul_f32_e32 v108, v99, v67
	v_fmac_f32_e32 v108, v98, v66
	v_fmac_f32_e32 v108, v100, v68
	v_fmac_f32_e32 v108, v101, v69
	v_add_f32_e32 v48, v48, v108
	ds_read_b128 v[2:5], v60 offset:36864
	ds_read_b128 v[6:9], v60 offset:40960
	ds_read_b128 v[10:13], v60 offset:45056
	ds_read_b128 v[14:17], v60 offset:49152
	ds_read_b128 v[18:21], v60 offset:53248
	ds_read_b128 v[22:25], v60 offset:57344
	ds_read_b128 v[26:29], v60 offset:61440
	ds_read_b128 v[94:97], v109
	s_waitcnt lgkmcnt(7)
	v_mul_f32_e32 v108, v3, v67
	v_fmac_f32_e32 v108, v2, v66
	v_fmac_f32_e32 v108, v4, v68
	v_fmac_f32_e32 v108, v5, v69
	v_add_f32_e32 v47, v47, v108
	s_waitcnt lgkmcnt(6)
	v_mul_f32_e32 v108, v7, v67
	v_fmac_f32_e32 v108, v6, v66
	v_fmac_f32_e32 v108, v8, v68
	v_fmac_f32_e32 v108, v9, v69
	v_add_f32_e32 v46, v46, v108
	s_waitcnt lgkmcnt(5)
	v_mul_f32_e32 v108, v11, v67
	v_fmac_f32_e32 v108, v10, v66
	v_fmac_f32_e32 v108, v12, v68
	v_fmac_f32_e32 v108, v13, v69
	v_add_f32_e32 v45, v45, v108
	s_waitcnt lgkmcnt(4)
	v_mul_f32_e32 v108, v15, v67
	v_fmac_f32_e32 v108, v14, v66
	v_fmac_f32_e32 v108, v16, v68
	v_fmac_f32_e32 v108, v17, v69
	v_add_f32_e32 v44, v44, v108
	s_waitcnt lgkmcnt(3)
	v_mul_f32_e32 v108, v19, v67
	v_fmac_f32_e32 v108, v18, v66
	v_fmac_f32_e32 v108, v20, v68
	v_fmac_f32_e32 v108, v21, v69
	v_add_f32_e32 v41, v41, v108
	s_waitcnt lgkmcnt(2)
	v_mul_f32_e32 v108, v23, v67
	v_fmac_f32_e32 v108, v22, v66
	v_fmac_f32_e32 v108, v24, v68
	v_fmac_f32_e32 v108, v25, v69
	v_add_f32_e32 v40, v40, v108
	s_waitcnt lgkmcnt(1)
	v_mul_f32_e32 v108, v27, v67
	v_fmac_f32_e32 v108, v26, v66
	v_fmac_f32_e32 v108, v28, v68
	v_fmac_f32_e32 v108, v29, v69
	v_add_f32_e32 v39, v39, v108
	s_waitcnt lgkmcnt(0)
	v_mul_f32_e32 v108, v95, v67
	v_fmac_f32_e32 v108, v94, v66
	v_fmac_f32_e32 v108, v96, v68
	v_fmac_f32_e32 v108, v97, v69
	v_add_f32_e32 v38, v38, v108
	v_add_u32_e32 v60, 16, v60
	s_waitcnt vmcnt(20)
	v_add_u32_e32 v109, 0x10000, v60
	ds_read_b128 v[2:5], v60
	ds_read_b128 v[6:9], v60 offset:4096
	ds_read_b128 v[10:13], v60 offset:8192
	ds_read_b128 v[14:17], v60 offset:12288
	ds_read_b128 v[18:21], v60 offset:16384
	ds_read_b128 v[22:25], v60 offset:20480
	ds_read_b128 v[26:29], v60 offset:24576
	ds_read_b128 v[94:97], v60 offset:28672
	ds_read_b128 v[98:101], v60 offset:32768
	s_waitcnt lgkmcnt(8)
	v_mul_f32_e32 v108, v3, v71
	v_fmac_f32_e32 v108, v2, v70
	v_fmac_f32_e32 v108, v4, v72
	v_fmac_f32_e32 v108, v5, v73
	v_add_f32_e32 v59, v59, v108
	s_waitcnt lgkmcnt(7)
	v_mul_f32_e32 v108, v7, v71
	v_fmac_f32_e32 v108, v6, v70
	v_fmac_f32_e32 v108, v8, v72
	v_fmac_f32_e32 v108, v9, v73
	v_add_f32_e32 v55, v55, v108
	s_waitcnt lgkmcnt(6)
	v_mul_f32_e32 v108, v11, v71
	v_fmac_f32_e32 v108, v10, v70
	v_fmac_f32_e32 v108, v12, v72
	v_fmac_f32_e32 v108, v13, v73
	v_add_f32_e32 v54, v54, v108
	s_waitcnt lgkmcnt(5)
	v_mul_f32_e32 v108, v15, v71
	v_fmac_f32_e32 v108, v14, v70
	v_fmac_f32_e32 v108, v16, v72
	v_fmac_f32_e32 v108, v17, v73
	v_add_f32_e32 v53, v53, v108
	s_waitcnt lgkmcnt(4)
	v_mul_f32_e32 v108, v19, v71
	v_fmac_f32_e32 v108, v18, v70
	v_fmac_f32_e32 v108, v20, v72
	v_fmac_f32_e32 v108, v21, v73
	v_add_f32_e32 v52, v52, v108
	s_waitcnt lgkmcnt(3)
	v_mul_f32_e32 v108, v23, v71
	v_fmac_f32_e32 v108, v22, v70
	v_fmac_f32_e32 v108, v24, v72
	v_fmac_f32_e32 v108, v25, v73
	v_add_f32_e32 v51, v51, v108
	s_waitcnt lgkmcnt(2)
	v_mul_f32_e32 v108, v27, v71
	v_fmac_f32_e32 v108, v26, v70
	v_fmac_f32_e32 v108, v28, v72
	v_fmac_f32_e32 v108, v29, v73
	v_add_f32_e32 v50, v50, v108
	s_waitcnt lgkmcnt(1)
	v_mul_f32_e32 v108, v95, v71
	v_fmac_f32_e32 v108, v94, v70
	v_fmac_f32_e32 v108, v96, v72
	v_fmac_f32_e32 v108, v97, v73
	v_add_f32_e32 v49, v49, v108
	s_waitcnt lgkmcnt(0)
	v_mul_f32_e32 v108, v99, v71
	v_fmac_f32_e32 v108, v98, v70
	v_fmac_f32_e32 v108, v100, v72
	v_fmac_f32_e32 v108, v101, v73
	v_add_f32_e32 v48, v48, v108
	ds_read_b128 v[2:5], v60 offset:36864
	ds_read_b128 v[6:9], v60 offset:40960
	ds_read_b128 v[10:13], v60 offset:45056
	ds_read_b128 v[14:17], v60 offset:49152
	ds_read_b128 v[18:21], v60 offset:53248
	ds_read_b128 v[22:25], v60 offset:57344
	ds_read_b128 v[26:29], v60 offset:61440
	ds_read_b128 v[94:97], v109
	s_waitcnt lgkmcnt(7)
; __device__ __forceinline__ void phase_init(const Params& P, unsigned char* lds) {
;     ...
;         for (int k = wave * 128; k < wave * 128 + 128; k += 4) {
;             const float w0 = W[(size_t)k * MODW], w1 = W[(size_t)(k + 1) * MODW], w2 = W[(size_t)(k + 2) * MODW], w3 = W[(size_t)(k + 3) * MODW];
; #pragma unroll
;             for (int bb = 0; bb < 17; ++bb) { const f32x4 s4 = *(const f32x4*)(sc + bb * DM + k); acc[bb] += s4.x * w0 + s4.y * w1 + s4.z * w2 + s4.w * w3; }
;         }
	v_mul_f32_e32 v108, v3, v71
	v_fmac_f32_e32 v108, v2, v70
	v_fmac_f32_e32 v108, v4, v72
	v_fmac_f32_e32 v108, v5, v73
	v_add_f32_e32 v47, v47, v108
	s_waitcnt lgkmcnt(6)
	v_mul_f32_e32 v108, v7, v71
	v_fmac_f32_e32 v108, v6, v70
	v_fmac_f32_e32 v108, v8, v72
	v_fmac_f32_e32 v108, v9, v73
	v_add_f32_e32 v46, v46, v108
	s_waitcnt lgkmcnt(5)
	v_mul_f32_e32 v108, v11, v71
	v_fmac_f32_e32 v108, v10, v70
	v_fmac_f32_e32 v108, v12, v72
	v_fmac_f32_e32 v108, v13, v73
	v_add_f32_e32 v45, v45, v108
	s_waitcnt lgkmcnt(4)
	v_mul_f32_e32 v108, v15, v71
	v_fmac_f32_e32 v108, v14, v70
	v_fmac_f32_e32 v108, v16, v72
	v_fmac_f32_e32 v108, v17, v73
	v_add_f32_e32 v44, v44, v108
	s_waitcnt lgkmcnt(3)
	v_mul_f32_e32 v108, v19, v71
	v_fmac_f32_e32 v108, v18, v70
	v_fmac_f32_e32 v108, v20, v72
	v_fmac_f32_e32 v108, v21, v73
	v_add_f32_e32 v41, v41, v108
	s_waitcnt lgkmcnt(2)
	v_mul_f32_e32 v108, v23, v71
	v_fmac_f32_e32 v108, v22, v70
	v_fmac_f32_e32 v108, v24, v72
	v_fmac_f32_e32 v108, v25, v73
	v_add_f32_e32 v40, v40, v108
	s_waitcnt lgkmcnt(1)
	v_mul_f32_e32 v108, v27, v71
	v_fmac_f32_e32 v108, v26, v70
	v_fmac_f32_e32 v108, v28, v72
	v_fmac_f32_e32 v108, v29, v73
	v_add_f32_e32 v39, v39, v108
	s_waitcnt lgkmcnt(0)
	v_mul_f32_e32 v108, v95, v71
	v_fmac_f32_e32 v108, v94, v70
	v_fmac_f32_e32 v108, v96, v72
	v_fmac_f32_e32 v108, v97, v73
	v_add_f32_e32 v38, v38, v108
	v_add_u32_e32 v60, 16, v60
	s_waitcnt vmcnt(16)
	v_add_u32_e32 v109, 0x10000, v60
	ds_read_b128 v[2:5], v60
	ds_read_b128 v[6:9], v60 offset:4096
	ds_read_b128 v[10:13], v60 offset:8192
	ds_read_b128 v[14:17], v60 offset:12288
	ds_read_b128 v[18:21], v60 offset:16384
	ds_read_b128 v[22:25], v60 offset:20480
	ds_read_b128 v[26:29], v60 offset:24576
	ds_read_b128 v[94:97], v60 offset:28672
	ds_read_b128 v[98:101], v60 offset:32768
	s_waitcnt lgkmcnt(8)
	v_mul_f32_e32 v108, v3, v75
	v_fmac_f32_e32 v108, v2, v74
	v_fmac_f32_e32 v108, v4, v76
	v_fmac_f32_e32 v108, v5, v77
	v_add_f32_e32 v59, v59, v108
	s_waitcnt lgkmcnt(7)
	v_mul_f32_e32 v108, v7, v75
	v_fmac_f32_e32 v108, v6, v74
	v_fmac_f32_e32 v108, v8, v76
	v_fmac_f32_e32 v108, v9, v77
	v_add_f32_e32 v55, v55, v108
	s_waitcnt lgkmcnt(6)
	v_mul_f32_e32 v108, v11, v75
	v_fmac_f32_e32 v108, v10, v74
	v_fmac_f32_e32 v108, v12, v76
	v_fmac_f32_e32 v108, v13, v77
	v_add_f32_e32 v54, v54, v108
	s_waitcnt lgkmcnt(5)
	v_mul_f32_e32 v108, v15, v75
	v_fmac_f32_e32 v108, v14, v74
	v_fmac_f32_e32 v108, v16, v76
	v_fmac_f32_e32 v108, v17, v77
	v_add_f32_e32 v53, v53, v108
	s_waitcnt lgkmcnt(4)
	v_mul_f32_e32 v108, v19, v75
	v_fmac_f32_e32 v108, v18, v74
	v_fmac_f32_e32 v108, v20, v76
	v_fmac_f32_e32 v108, v21, v77
	v_add_f32_e32 v52, v52, v108
	s_waitcnt lgkmcnt(3)
	v_mul_f32_e32 v108, v23, v75
	v_fmac_f32_e32 v108, v22, v74
	v_fmac_f32_e32 v108, v24, v76
	v_fmac_f32_e32 v108, v25, v77
	v_add_f32_e32 v51, v51, v108
	s_waitcnt lgkmcnt(2)
	v_mul_f32_e32 v108, v27, v75
	v_fmac_f32_e32 v108, v26, v74
	v_fmac_f32_e32 v108, v28, v76
	v_fmac_f32_e32 v108, v29, v77
	v_add_f32_e32 v50, v50, v108
	s_waitcnt lgkmcnt(1)
	v_mul_f32_e32 v108, v95, v75
	v_fmac_f32_e32 v108, v94, v74
	v_fmac_f32_e32 v108, v96, v76
	v_fmac_f32_e32 v108, v97, v77
	v_add_f32_e32 v49, v49, v108
	s_waitcnt lgkmcnt(0)
	v_mul_f32_e32 v108, v99, v75
	v_fmac_f32_e32 v108, v98, v74
	v_fmac_f32_e32 v108, v100, v76
	v_fmac_f32_e32 v108, v101, v77
	v_add_f32_e32 v48, v48, v108
	ds_read_b128 v[2:5], v60 offset:36864
	ds_read_b128 v[6:9], v60 offset:40960
	ds_read_b128 v[10:13], v60 offset:45056
	ds_read_b128 v[14:17], v60 offset:49152
	ds_read_b128 v[18:21], v60 offset:53248
	ds_read_b128 v[22:25], v60 offset:57344
	ds_read_b128 v[26:29], v60 offset:61440
	ds_read_b128 v[94:97], v109
	s_waitcnt lgkmcnt(7)
	v_mul_f32_e32 v108, v3, v75
	v_fmac_f32_e32 v108, v2, v74
	v_fmac_f32_e32 v108, v4, v76
	v_fmac_f32_e32 v108, v5, v77
	v_add_f32_e32 v47, v47, v108
	s_waitcnt lgkmcnt(6)
	v_mul_f32_e32 v108, v7, v75
	v_fmac_f32_e32 v108, v6, v74
	v_fmac_f32_e32 v108, v8, v76
	v_fmac_f32_e32 v108, v9, v77
	v_add_f32_e32 v46, v46, v108
	s_waitcnt lgkmcnt(5)
	v_mul_f32_e32 v108, v11, v75
	v_fmac_f32_e32 v108, v10, v74
	v_fmac_f32_e32 v108, v12, v76
	v_fmac_f32_e32 v108, v13, v77
	v_add_f32_e32 v45, v45, v108
	s_waitcnt lgkmcnt(4)
	v_mul_f32_e32 v108, v15, v75
	v_fmac_f32_e32 v108, v14, v74
	v_fmac_f32_e32 v108, v16, v76
	v_fmac_f32_e32 v108, v17, v77
	v_add_f32_e32 v44, v44, v108
	s_waitcnt lgkmcnt(3)
	v_mul_f32_e32 v108, v19, v75
	v_fmac_f32_e32 v108, v18, v74
	v_fmac_f32_e32 v108, v20, v76
	v_fmac_f32_e32 v108, v21, v77
	v_add_f32_e32 v41, v41, v108
	s_waitcnt lgkmcnt(2)
	v_mul_f32_e32 v108, v23, v75
	v_fmac_f32_e32 v108, v22, v74
	v_fmac_f32_e32 v108, v24, v76
	v_fmac_f32_e32 v108, v25, v77
	v_add_f32_e32 v40, v40, v108
	s_waitcnt lgkmcnt(1)
	v_mul_f32_e32 v108, v27, v75
	v_fmac_f32_e32 v108, v26, v74
	v_fmac_f32_e32 v108, v28, v76
	v_fmac_f32_e32 v108, v29, v77
	v_add_f32_e32 v39, v39, v108
	s_waitcnt lgkmcnt(0)
	v_mul_f32_e32 v108, v95, v75
	v_fmac_f32_e32 v108, v94, v74
	v_fmac_f32_e32 v108, v96, v76
	v_fmac_f32_e32 v108, v97, v77
	v_add_f32_e32 v38, v38, v108
	v_add_u32_e32 v60, 16, v60
	s_waitcnt vmcnt(12)
	v_add_u32_e32 v109, 0x10000, v60
	ds_read_b128 v[2:5], v60
	ds_read_b128 v[6:9], v60 offset:4096
	ds_read_b128 v[10:13], v60 offset:8192
	ds_read_b128 v[14:17], v60 offset:12288
	ds_read_b128 v[18:21], v60 offset:16384
	ds_read_b128 v[22:25], v60 offset:20480
	ds_read_b128 v[26:29], v60 offset:24576
	ds_read_b128 v[94:97], v60 offset:28672
	ds_read_b128 v[98:101], v60 offset:32768
	s_waitcnt lgkmcnt(8)
	v_mul_f32_e32 v108, v3, v79
	v_fmac_f32_e32 v108, v2, v78
	v_fmac_f32_e32 v108, v4, v80
	v_fmac_f32_e32 v108, v5, v81
	v_add_f32_e32 v59, v59, v108
	s_waitcnt lgkmcnt(7)
; __device__ __forceinline__ void phase_init(const Params& P, unsigned char* lds) {
;     ...
;         for (int k = wave * 128; k < wave * 128 + 128; k += 4) {
;             const float w0 = W[(size_t)k * MODW], w1 = W[(size_t)(k + 1) * MODW], w2 = W[(size_t)(k + 2) * MODW], w3 = W[(size_t)(k + 3) * MODW];
; #pragma unroll
;             for (int bb = 0; bb < 17; ++bb) { const f32x4 s4 = *(const f32x4*)(sc + bb * DM + k); acc[bb] += s4.x * w0 + s4.y * w1 + s4.z * w2 + s4.w * w3; }
;         }
	v_mul_f32_e32 v108, v7, v79
	v_fmac_f32_e32 v108, v6, v78
	v_fmac_f32_e32 v108, v8, v80
	v_fmac_f32_e32 v108, v9, v81
	v_add_f32_e32 v55, v55, v108
	s_waitcnt lgkmcnt(6)
	v_mul_f32_e32 v108, v11, v79
	v_fmac_f32_e32 v108, v10, v78
	v_fmac_f32_e32 v108, v12, v80
	v_fmac_f32_e32 v108, v13, v81
	v_add_f32_e32 v54, v54, v108
	s_waitcnt lgkmcnt(5)
	v_mul_f32_e32 v108, v15, v79
	v_fmac_f32_e32 v108, v14, v78
	v_fmac_f32_e32 v108, v16, v80
	v_fmac_f32_e32 v108, v17, v81
	v_add_f32_e32 v53, v53, v108
	s_waitcnt lgkmcnt(4)
	v_mul_f32_e32 v108, v19, v79
	v_fmac_f32_e32 v108, v18, v78
	v_fmac_f32_e32 v108, v20, v80
	v_fmac_f32_e32 v108, v21, v81
	v_add_f32_e32 v52, v52, v108
	s_waitcnt lgkmcnt(3)
	v_mul_f32_e32 v108, v23, v79
	v_fmac_f32_e32 v108, v22, v78
	v_fmac_f32_e32 v108, v24, v80
	v_fmac_f32_e32 v108, v25, v81
	v_add_f32_e32 v51, v51, v108
	s_waitcnt lgkmcnt(2)
	v_mul_f32_e32 v108, v27, v79
	v_fmac_f32_e32 v108, v26, v78
	v_fmac_f32_e32 v108, v28, v80
	v_fmac_f32_e32 v108, v29, v81
	v_add_f32_e32 v50, v50, v108
	s_waitcnt lgkmcnt(1)
	v_mul_f32_e32 v108, v95, v79
	v_fmac_f32_e32 v108, v94, v78
	v_fmac_f32_e32 v108, v96, v80
	v_fmac_f32_e32 v108, v97, v81
	v_add_f32_e32 v49, v49, v108
	s_waitcnt lgkmcnt(0)
	v_mul_f32_e32 v108, v99, v79
	v_fmac_f32_e32 v108, v98, v78
	v_fmac_f32_e32 v108, v100, v80
	v_fmac_f32_e32 v108, v101, v81
	v_add_f32_e32 v48, v48, v108
	ds_read_b128 v[2:5], v60 offset:36864
	ds_read_b128 v[6:9], v60 offset:40960
	ds_read_b128 v[10:13], v60 offset:45056
	ds_read_b128 v[14:17], v60 offset:49152
	ds_read_b128 v[18:21], v60 offset:53248
	ds_read_b128 v[22:25], v60 offset:57344
	ds_read_b128 v[26:29], v60 offset:61440
	ds_read_b128 v[94:97], v109
	s_waitcnt lgkmcnt(7)
	v_mul_f32_e32 v108, v3, v79
	v_fmac_f32_e32 v108, v2, v78
	v_fmac_f32_e32 v108, v4, v80
	v_fmac_f32_e32 v108, v5, v81
	v_add_f32_e32 v47, v47, v108
	s_waitcnt lgkmcnt(6)
	v_mul_f32_e32 v108, v7, v79
	v_fmac_f32_e32 v108, v6, v78
	v_fmac_f32_e32 v108, v8, v80
	v_fmac_f32_e32 v108, v9, v81
	v_add_f32_e32 v46, v46, v108
	s_waitcnt lgkmcnt(5)
	v_mul_f32_e32 v108, v11, v79
	v_fmac_f32_e32 v108, v10, v78
	v_fmac_f32_e32 v108, v12, v80
	v_fmac_f32_e32 v108, v13, v81
	v_add_f32_e32 v45, v45, v108
	s_waitcnt lgkmcnt(4)
	v_mul_f32_e32 v108, v15, v79
	v_fmac_f32_e32 v108, v14, v78
	v_fmac_f32_e32 v108, v16, v80
	v_fmac_f32_e32 v108, v17, v81
	v_add_f32_e32 v44, v44, v108
	s_waitcnt lgkmcnt(3)
	v_mul_f32_e32 v108, v19, v79
	v_fmac_f32_e32 v108, v18, v78
	v_fmac_f32_e32 v108, v20, v80
	v_fmac_f32_e32 v108, v21, v81
	v_add_f32_e32 v41, v41, v108
	s_waitcnt lgkmcnt(2)
	v_mul_f32_e32 v108, v23, v79
	v_fmac_f32_e32 v108, v22, v78
	v_fmac_f32_e32 v108, v24, v80
	v_fmac_f32_e32 v108, v25, v81
	v_add_f32_e32 v40, v40, v108
	s_waitcnt lgkmcnt(1)
	v_mul_f32_e32 v108, v27, v79
	v_fmac_f32_e32 v108, v26, v78
	v_fmac_f32_e32 v108, v28, v80
	v_fmac_f32_e32 v108, v29, v81
	v_add_f32_e32 v39, v39, v108
	s_waitcnt lgkmcnt(0)
	v_mul_f32_e32 v108, v95, v79
	v_fmac_f32_e32 v108, v94, v78
	v_fmac_f32_e32 v108, v96, v80
	v_fmac_f32_e32 v108, v97, v81
	v_add_f32_e32 v38, v38, v108
	v_add_u32_e32 v60, 16, v60
	s_waitcnt vmcnt(8)
	v_add_u32_e32 v109, 0x10000, v60
	ds_read_b128 v[2:5], v60
	ds_read_b128 v[6:9], v60 offset:4096
	ds_read_b128 v[10:13], v60 offset:8192
	ds_read_b128 v[14:17], v60 offset:12288
	ds_read_b128 v[18:21], v60 offset:16384
	ds_read_b128 v[22:25], v60 offset:20480
	ds_read_b128 v[26:29], v60 offset:24576
	ds_read_b128 v[94:97], v60 offset:28672
	ds_read_b128 v[98:101], v60 offset:32768
	s_waitcnt lgkmcnt(8)
	v_mul_f32_e32 v108, v3, v83
	v_fmac_f32_e32 v108, v2, v82
	v_fmac_f32_e32 v108, v4, v84
	v_fmac_f32_e32 v108, v5, v85
	v_add_f32_e32 v59, v59, v108
	s_waitcnt lgkmcnt(7)
	v_mul_f32_e32 v108, v7, v83
	v_fmac_f32_e32 v108, v6, v82
	v_fmac_f32_e32 v108, v8, v84
	v_fmac_f32_e32 v108, v9, v85
	v_add_f32_e32 v55, v55, v108
	s_waitcnt lgkmcnt(6)
	v_mul_f32_e32 v108, v11, v83
	v_fmac_f32_e32 v108, v10, v82
	v_fmac_f32_e32 v108, v12, v84
	v_fmac_f32_e32 v108, v13, v85
	v_add_f32_e32 v54, v54, v108
	s_waitcnt lgkmcnt(5)
	v_mul_f32_e32 v108, v15, v83
	v_fmac_f32_e32 v108, v14, v82
	v_fmac_f32_e32 v108, v16, v84
	v_fmac_f32_e32 v108, v17, v85
	v_add_f32_e32 v53, v53, v108
	s_waitcnt lgkmcnt(4)
	v_mul_f32_e32 v108, v19, v83
	v_fmac_f32_e32 v108, v18, v82
	v_fmac_f32_e32 v108, v20, v84
	v_fmac_f32_e32 v108, v21, v85
	v_add_f32_e32 v52, v52, v108
	s_waitcnt lgkmcnt(3)
	v_mul_f32_e32 v108, v23, v83
	v_fmac_f32_e32 v108, v22, v82
	v_fmac_f32_e32 v108, v24, v84
	v_fmac_f32_e32 v108, v25, v85
	v_add_f32_e32 v51, v51, v108
	s_waitcnt lgkmcnt(2)
	v_mul_f32_e32 v108, v27, v83
	v_fmac_f32_e32 v108, v26, v82
	v_fmac_f32_e32 v108, v28, v84
	v_fmac_f32_e32 v108, v29, v85
	v_add_f32_e32 v50, v50, v108
	s_waitcnt lgkmcnt(1)
	v_mul_f32_e32 v108, v95, v83
	v_fmac_f32_e32 v108, v94, v82
	v_fmac_f32_e32 v108, v96, v84
	v_fmac_f32_e32 v108, v97, v85
	v_add_f32_e32 v49, v49, v108
	s_waitcnt lgkmcnt(0)
	v_mul_f32_e32 v108, v99, v83
	v_fmac_f32_e32 v108, v98, v82
	v_fmac_f32_e32 v108, v100, v84
	v_fmac_f32_e32 v108, v101, v85
	v_add_f32_e32 v48, v48, v108
	ds_read_b128 v[2:5], v60 offset:36864
	ds_read_b128 v[6:9], v60 offset:40960
	ds_read_b128 v[10:13], v60 offset:45056
	ds_read_b128 v[14:17], v60 offset:49152
	ds_read_b128 v[18:21], v60 offset:53248
	ds_read_b128 v[22:25], v60 offset:57344
	ds_read_b128 v[26:29], v60 offset:61440
	ds_read_b128 v[94:97], v109
	s_waitcnt lgkmcnt(7)
	v_mul_f32_e32 v108, v3, v83
	v_fmac_f32_e32 v108, v2, v82
	v_fmac_f32_e32 v108, v4, v84
	v_fmac_f32_e32 v108, v5, v85
	v_add_f32_e32 v47, v47, v108
	s_waitcnt lgkmcnt(6)
; __device__ __forceinline__ void phase_init(const Params& P, unsigned char* lds) {
;     ...
;         for (int k = wave * 128; k < wave * 128 + 128; k += 4) {
;             const float w0 = W[(size_t)k * MODW], w1 = W[(size_t)(k + 1) * MODW], w2 = W[(size_t)(k + 2) * MODW], w3 = W[(size_t)(k + 3) * MODW];
; #pragma unroll
;             for (int bb = 0; bb < 17; ++bb) { const f32x4 s4 = *(const f32x4*)(sc + bb * DM + k); acc[bb] += s4.x * w0 + s4.y * w1 + s4.z * w2 + s4.w * w3; }
;         }
	v_mul_f32_e32 v108, v7, v83
	v_fmac_f32_e32 v108, v6, v82
	v_fmac_f32_e32 v108, v8, v84
	v_fmac_f32_e32 v108, v9, v85
	v_add_f32_e32 v46, v46, v108
	s_waitcnt lgkmcnt(5)
	v_mul_f32_e32 v108, v11, v83
	v_fmac_f32_e32 v108, v10, v82
	v_fmac_f32_e32 v108, v12, v84
	v_fmac_f32_e32 v108, v13, v85
	v_add_f32_e32 v45, v45, v108
	s_waitcnt lgkmcnt(4)
	v_mul_f32_e32 v108, v15, v83
	v_fmac_f32_e32 v108, v14, v82
	v_fmac_f32_e32 v108, v16, v84
	v_fmac_f32_e32 v108, v17, v85
	v_add_f32_e32 v44, v44, v108
	s_waitcnt lgkmcnt(3)
	v_mul_f32_e32 v108, v19, v83
	v_fmac_f32_e32 v108, v18, v82
	v_fmac_f32_e32 v108, v20, v84
	v_fmac_f32_e32 v108, v21, v85
	v_add_f32_e32 v41, v41, v108
	s_waitcnt lgkmcnt(2)
	v_mul_f32_e32 v108, v23, v83
	v_fmac_f32_e32 v108, v22, v82
	v_fmac_f32_e32 v108, v24, v84
	v_fmac_f32_e32 v108, v25, v85
	v_add_f32_e32 v40, v40, v108
	s_waitcnt lgkmcnt(1)
	v_mul_f32_e32 v108, v27, v83
	v_fmac_f32_e32 v108, v26, v82
	v_fmac_f32_e32 v108, v28, v84
	v_fmac_f32_e32 v108, v29, v85
	v_add_f32_e32 v39, v39, v108
	s_waitcnt lgkmcnt(0)
	v_mul_f32_e32 v108, v95, v83
	v_fmac_f32_e32 v108, v94, v82
	v_fmac_f32_e32 v108, v96, v84
	v_fmac_f32_e32 v108, v97, v85
	v_add_f32_e32 v38, v38, v108
	v_add_u32_e32 v60, 16, v60
	s_waitcnt vmcnt(4)
	v_add_u32_e32 v109, 0x10000, v60
	ds_read_b128 v[2:5], v60
	ds_read_b128 v[6:9], v60 offset:4096
	ds_read_b128 v[10:13], v60 offset:8192
	ds_read_b128 v[14:17], v60 offset:12288
	ds_read_b128 v[18:21], v60 offset:16384
	ds_read_b128 v[22:25], v60 offset:20480
	ds_read_b128 v[26:29], v60 offset:24576
	ds_read_b128 v[94:97], v60 offset:28672
	ds_read_b128 v[98:101], v60 offset:32768
	s_waitcnt lgkmcnt(8)
	v_mul_f32_e32 v108, v3, v87
	v_fmac_f32_e32 v108, v2, v86
	v_fmac_f32_e32 v108, v4, v88
	v_fmac_f32_e32 v108, v5, v89
	v_add_f32_e32 v59, v59, v108
	s_waitcnt lgkmcnt(7)
	v_mul_f32_e32 v108, v7, v87
	v_fmac_f32_e32 v108, v6, v86
	v_fmac_f32_e32 v108, v8, v88
	v_fmac_f32_e32 v108, v9, v89
	v_add_f32_e32 v55, v55, v108
	s_waitcnt lgkmcnt(6)
	v_mul_f32_e32 v108, v11, v87
	v_fmac_f32_e32 v108, v10, v86
	v_fmac_f32_e32 v108, v12, v88
	v_fmac_f32_e32 v108, v13, v89
	v_add_f32_e32 v54, v54, v108
	s_waitcnt lgkmcnt(5)
	v_mul_f32_e32 v108, v15, v87
	v_fmac_f32_e32 v108, v14, v86
	v_fmac_f32_e32 v108, v16, v88
	v_fmac_f32_e32 v108, v17, v89
	v_add_f32_e32 v53, v53, v108
	s_waitcnt lgkmcnt(4)
	v_mul_f32_e32 v108, v19, v87
	v_fmac_f32_e32 v108, v18, v86
	v_fmac_f32_e32 v108, v20, v88
	v_fmac_f32_e32 v108, v21, v89
	v_add_f32_e32 v52, v52, v108
	s_waitcnt lgkmcnt(3)
	v_mul_f32_e32 v108, v23, v87
	v_fmac_f32_e32 v108, v22, v86
	v_fmac_f32_e32 v108, v24, v88
	v_fmac_f32_e32 v108, v25, v89
	v_add_f32_e32 v51, v51, v108
	s_waitcnt lgkmcnt(2)
	v_mul_f32_e32 v108, v27, v87
	v_fmac_f32_e32 v108, v26, v86
	v_fmac_f32_e32 v108, v28, v88
	v_fmac_f32_e32 v108, v29, v89
	v_add_f32_e32 v50, v50, v108
	s_waitcnt lgkmcnt(1)
	v_mul_f32_e32 v108, v95, v87
	v_fmac_f32_e32 v108, v94, v86
	v_fmac_f32_e32 v108, v96, v88
	v_fmac_f32_e32 v108, v97, v89
	v_add_f32_e32 v49, v49, v108
	s_waitcnt lgkmcnt(0)
	v_mul_f32_e32 v108, v99, v87
	v_fmac_f32_e32 v108, v98, v86
	v_fmac_f32_e32 v108, v100, v88
	v_fmac_f32_e32 v108, v101, v89
	v_add_f32_e32 v48, v48, v108
	ds_read_b128 v[2:5], v60 offset:36864
	ds_read_b128 v[6:9], v60 offset:40960
	ds_read_b128 v[10:13], v60 offset:45056
	ds_read_b128 v[14:17], v60 offset:49152
	ds_read_b128 v[18:21], v60 offset:53248
	ds_read_b128 v[22:25], v60 offset:57344
	ds_read_b128 v[26:29], v60 offset:61440
	ds_read_b128 v[94:97], v109
	s_waitcnt lgkmcnt(7)
	v_mul_f32_e32 v108, v3, v87
	v_fmac_f32_e32 v108, v2, v86
	v_fmac_f32_e32 v108, v4, v88
	v_fmac_f32_e32 v108, v5, v89
	v_add_f32_e32 v47, v47, v108
	s_waitcnt lgkmcnt(6)
	v_mul_f32_e32 v108, v7, v87
	v_fmac_f32_e32 v108, v6, v86
	v_fmac_f32_e32 v108, v8, v88
	v_fmac_f32_e32 v108, v9, v89
	v_add_f32_e32 v46, v46, v108
	s_waitcnt lgkmcnt(5)
	v_mul_f32_e32 v108, v11, v87
	v_fmac_f32_e32 v108, v10, v86
	v_fmac_f32_e32 v108, v12, v88
	v_fmac_f32_e32 v108, v13, v89
	v_add_f32_e32 v45, v45, v108
	s_waitcnt lgkmcnt(4)
	v_mul_f32_e32 v108, v15, v87
	v_fmac_f32_e32 v108, v14, v86
	v_fmac_f32_e32 v108, v16, v88
	v_fmac_f32_e32 v108, v17, v89
	v_add_f32_e32 v44, v44, v108
	s_waitcnt lgkmcnt(3)
	v_mul_f32_e32 v108, v19, v87
	v_fmac_f32_e32 v108, v18, v86
	v_fmac_f32_e32 v108, v20, v88
	v_fmac_f32_e32 v108, v21, v89
	v_add_f32_e32 v41, v41, v108
	s_waitcnt lgkmcnt(2)
	v_mul_f32_e32 v108, v23, v87
	v_fmac_f32_e32 v108, v22, v86
	v_fmac_f32_e32 v108, v24, v88
	v_fmac_f32_e32 v108, v25, v89
	v_add_f32_e32 v40, v40, v108
	s_waitcnt lgkmcnt(1)
	v_mul_f32_e32 v108, v27, v87
	v_fmac_f32_e32 v108, v26, v86
	v_fmac_f32_e32 v108, v28, v88
	v_fmac_f32_e32 v108, v29, v89
	v_add_f32_e32 v39, v39, v108
	s_waitcnt lgkmcnt(0)
; __device__ __forceinline__ void phase_init(const Params& P, unsigned char* lds) {
;     ...
;         for (int k = wave * 128; k < wave * 128 + 128; k += 4) {
;             const float w0 = W[(size_t)k * MODW], w1 = W[(size_t)(k + 1) * MODW], w2 = W[(size_t)(k + 2) * MODW], w3 = W[(size_t)(k + 3) * MODW];
; #pragma unroll
;             for (int bb = 0; bb < 17; ++bb) { const f32x4 s4 = *(const f32x4*)(sc + bb * DM + k); acc[bb] += s4.x * w0 + s4.y * w1 + s4.z * w2 + s4.w * w3; }
;         }
; #pragma unroll
;         for (int bb = 0; bb < 17; ++bb) red[(wave * 17 + bb) * 64 + lane] = acc[bb];
;         __syncthreads();
;         for (int i = tid; i < 17 * 64; i += 512) { const int bb = i >> 6, n = i & 63; float s = 0.f;
; #pragma unroll
;             for (int w = 0; w < 8; ++w) s += red[(w * 17 + bb) * 64 + n];
;             mod[((size_t)l * 17 + bb) * MODW + n0 + n] = s + P.b_mod[(size_t)l * MODW + n0 + n]; }
	v_mul_f32_e32 v108, v95, v87
	v_fmac_f32_e32 v108, v94, v86
	v_fmac_f32_e32 v108, v96, v88
	v_fmac_f32_e32 v108, v97, v89
	v_add_f32_e32 v38, v38, v108
	v_add_u32_e32 v60, 16, v60
	s_waitcnt vmcnt(0)
	v_add_u32_e32 v109, 0x10000, v60
	ds_read_b128 v[2:5], v60
	ds_read_b128 v[6:9], v60 offset:4096
	ds_read_b128 v[10:13], v60 offset:8192
	ds_read_b128 v[14:17], v60 offset:12288
	ds_read_b128 v[18:21], v60 offset:16384
	ds_read_b128 v[22:25], v60 offset:20480
	ds_read_b128 v[26:29], v60 offset:24576
	ds_read_b128 v[94:97], v60 offset:28672
	ds_read_b128 v[98:101], v60 offset:32768
	s_waitcnt lgkmcnt(8)
	v_mul_f32_e32 v108, v3, v91
	v_fmac_f32_e32 v108, v2, v90
	v_fmac_f32_e32 v108, v4, v92
	v_fmac_f32_e32 v108, v5, v93
	v_add_f32_e32 v59, v59, v108
	s_waitcnt lgkmcnt(7)
	v_mul_f32_e32 v108, v7, v91
	v_fmac_f32_e32 v108, v6, v90
	v_fmac_f32_e32 v108, v8, v92
	v_fmac_f32_e32 v108, v9, v93
	v_add_f32_e32 v55, v55, v108
	s_waitcnt lgkmcnt(6)
	v_mul_f32_e32 v108, v11, v91
	v_fmac_f32_e32 v108, v10, v90
	v_fmac_f32_e32 v108, v12, v92
	v_fmac_f32_e32 v108, v13, v93
	v_add_f32_e32 v54, v54, v108
	s_waitcnt lgkmcnt(5)
	v_mul_f32_e32 v108, v15, v91
	v_fmac_f32_e32 v108, v14, v90
	v_fmac_f32_e32 v108, v16, v92
	v_fmac_f32_e32 v108, v17, v93
	v_add_f32_e32 v53, v53, v108
	s_waitcnt lgkmcnt(4)
	v_mul_f32_e32 v108, v19, v91
	v_fmac_f32_e32 v108, v18, v90
	v_fmac_f32_e32 v108, v20, v92
	v_fmac_f32_e32 v108, v21, v93
	v_add_f32_e32 v52, v52, v108
	s_waitcnt lgkmcnt(3)
	v_mul_f32_e32 v108, v23, v91
	v_fmac_f32_e32 v108, v22, v90
	v_fmac_f32_e32 v108, v24, v92
	v_fmac_f32_e32 v108, v25, v93
	v_add_f32_e32 v51, v51, v108
	s_waitcnt lgkmcnt(2)
	v_mul_f32_e32 v108, v27, v91
	v_fmac_f32_e32 v108, v26, v90
	v_fmac_f32_e32 v108, v28, v92
	v_fmac_f32_e32 v108, v29, v93
	v_add_f32_e32 v50, v50, v108
	s_waitcnt lgkmcnt(1)
	v_mul_f32_e32 v108, v95, v91
	v_fmac_f32_e32 v108, v94, v90
	v_fmac_f32_e32 v108, v96, v92
	v_fmac_f32_e32 v108, v97, v93
	v_add_f32_e32 v49, v49, v108
	s_waitcnt lgkmcnt(0)
	v_mul_f32_e32 v108, v99, v91
	v_fmac_f32_e32 v108, v98, v90
	v_fmac_f32_e32 v108, v100, v92
	v_fmac_f32_e32 v108, v101, v93
	v_add_f32_e32 v48, v48, v108
	ds_read_b128 v[2:5], v60 offset:36864
	ds_read_b128 v[6:9], v60 offset:40960
	ds_read_b128 v[10:13], v60 offset:45056
	ds_read_b128 v[14:17], v60 offset:49152
	ds_read_b128 v[18:21], v60 offset:53248
	ds_read_b128 v[22:25], v60 offset:57344
	ds_read_b128 v[26:29], v60 offset:61440
	ds_read_b128 v[94:97], v109
	s_waitcnt lgkmcnt(7)
	v_mul_f32_e32 v108, v3, v91
	v_fmac_f32_e32 v108, v2, v90
	v_fmac_f32_e32 v108, v4, v92
	v_fmac_f32_e32 v108, v5, v93
	v_add_f32_e32 v47, v47, v108
	s_waitcnt lgkmcnt(6)
	v_mul_f32_e32 v108, v7, v91
	v_fmac_f32_e32 v108, v6, v90
	v_fmac_f32_e32 v108, v8, v92
	v_fmac_f32_e32 v108, v9, v93
	v_add_f32_e32 v46, v46, v108
	s_waitcnt lgkmcnt(5)
	v_mul_f32_e32 v108, v11, v91
	v_fmac_f32_e32 v108, v10, v90
	v_fmac_f32_e32 v108, v12, v92
	v_fmac_f32_e32 v108, v13, v93
	v_add_f32_e32 v45, v45, v108
	s_waitcnt lgkmcnt(4)
	v_mul_f32_e32 v108, v15, v91
	v_fmac_f32_e32 v108, v14, v90
	v_fmac_f32_e32 v108, v16, v92
	v_fmac_f32_e32 v108, v17, v93
	v_add_f32_e32 v44, v44, v108
	s_waitcnt lgkmcnt(3)
	v_mul_f32_e32 v108, v19, v91
	v_fmac_f32_e32 v108, v18, v90
	v_fmac_f32_e32 v108, v20, v92
	v_fmac_f32_e32 v108, v21, v93
	v_add_f32_e32 v41, v41, v108
	s_waitcnt lgkmcnt(2)
	v_mul_f32_e32 v108, v23, v91
	v_fmac_f32_e32 v108, v22, v90
	v_fmac_f32_e32 v108, v24, v92
	v_fmac_f32_e32 v108, v25, v93
	v_add_f32_e32 v40, v40, v108
	s_waitcnt lgkmcnt(1)
	v_mul_f32_e32 v108, v27, v91
	v_fmac_f32_e32 v108, v26, v90
	v_fmac_f32_e32 v108, v28, v92
	v_fmac_f32_e32 v108, v29, v93
	v_add_f32_e32 v39, v39, v108
	s_waitcnt lgkmcnt(0)
	v_mul_f32_e32 v108, v95, v91
	v_fmac_f32_e32 v108, v94, v90
	v_fmac_f32_e32 v108, v96, v92
	v_fmac_f32_e32 v108, v97, v93
	v_add_f32_e32 v38, v38, v108
	v_add_u32_e32 v60, 16, v60
	s_mov_b32 s14, 0
	s_or_b64 exec, exec, s[14:15]
	ds_write2st64_b32 v58, v59, v55 offset1:1
	ds_write2st64_b32 v58, v54, v53 offset0:2 offset1:3
	ds_write2st64_b32 v58, v52, v51 offset0:4 offset1:5
	ds_write2st64_b32 v58, v50, v49 offset0:6 offset1:7
	ds_write2st64_b32 v58, v48, v47 offset0:8 offset1:9
	ds_write2st64_b32 v58, v46, v45 offset0:10 offset1:11
	ds_write2st64_b32 v58, v44, v41 offset0:12 offset1:13
	ds_write2st64_b32 v58, v40, v39 offset0:14 offset1:15
	ds_write_b32 v58, v38 offset:4096
	s_waitcnt lgkmcnt(0)
	s_barrier
	s_and_saveexec_b64 s[14:15], vcc
	s_cbranch_execz .LBB0_32
	s_mul_i32 s5, s16, 0x6000
	s_mul_hi_i32 s4, s16, 0x6000
	s_add_u32 s5, s12, s5
	s_addc_u32 s17, s13, s4
	s_add_u32 s4, s5, s10
	s_addc_u32 s5, s17, s11
	s_mul_hi_i32 s17, s16, 17
	s_mul_i32 s16, s16, 17
	v_lshl_add_u64 v[2:3], s[4:5], 0, v[32:33]
	v_lshl_add_u64 v[4:5], v[34:35], 0, s[10:11]
	s_mov_b64 s[10:11], 0
	v_mov_b32_e32 v6, v30
